# baseline (speedup 1.0000x reference)
; #define PG8_STAGE(bufoff, gbase, voff) do { _Pragma("unroll") for (int _i = 0; _i < 2; ++_i) \
;         __builtin_amdgcn_global_load_lds((const unsigned*)((const char*)(gbase) + (voff)[_i]), (PG8_LAS unsigned*)(lds + (bufoff) + ldsw + _i * 8192), 16, 0, 0); } while (0)
; #define PG8_LDA(dst, b, h) do { _Pragma("unroll") for (int m = 0; m < 4; ++m) _Pragma("unroll") for (int k = 0; k < 2; ++k) dst[m][k] = *(const PG8_LAS bf16x8*)(lds + PG8_SA(b, h) + aoff + m * 2048 + k * 1024); } while (0)
; #define PG8_LDB(dst, b, h) do { _Pragma("unroll") for (int n = 0; n < 2; ++n) _Pragma("unroll") for (int k = 0; k < 2; ++k) dst[n][k] = *(const PG8_LAS bf16x8*)(lds + PG8_SB(b, h) + boff + n * 2048 + k * 1024); } while (0)
; #define PG8_MMA(ai, bj, At, Bt) do { __builtin_amdgcn_s_setprio(1); _Pragma("unroll") for (int m = 0; m < 4; ++m) _Pragma("unroll") for (int n = 0; n < 2; ++n) _Pragma("unroll") for (int k = 0; k < 2; ++k) \
;         acc[ai][bj][m][n] = __builtin_amdgcn_mfma_f32_16x16x32_bf16(Bt[n][k], At[m][k], acc[ai][bj][m][n], 0, 0, 0); __builtin_amdgcn_s_setprio(0); } while (0)
; #define PG8_WAIT_V(n) asm volatile("s_waitcnt vmcnt(" #n ")" ::: "memory")
; #define PG8_WAIT_L(n) asm volatile("s_waitcnt lgkmcnt(" #n ")" ::: "memory")
; #define PG8_BAR __builtin_amdgcn_s_barrier()
; #define PG8_SCHED __builtin_amdgcn_sched_barrier(0)
; template <class Epi, class Sched, bool ALIGN_EPI = false, bool SP2 = false>
; __device__ __forceinline__ void gemm_phase(PG8_LAS unsigned char* lds, const Gemm g, const Sched& S, const Epi& E, const int wv) {
;     ...
;             const bool last = (t == nt - 2);
;             const char* a1 = cA + (size_t)(t + 1) * kstep;
;             const char* a2 = last ? nA : cA + (size_t)(t + 2) * kstep; const char* b2 = last ? nB : cB + (size_t)(t + 2) * kstep;
;             const char* a3 = a2 + kstep; const char* b3 = b2 + kstep;
;             if (last && has_next) S.a_ready(nxt);
;             if constexpr (SP2) {
;             PG8_LDB(B0, 0, 0); PG8_LDB(B1, 0, 1); PG8_SCHED; PG8_LDA(At, 0, 0); PG8_STAGE(PG8_SA(1, 1), a1 + hstep, voffA);
;             PG8_WAIT_V(8); PG8_WAIT_L(0); PG8_BAR; PG8_MMA(0, 0, At, B0); PG8_MMA(0, 1, At, B1); PG8_BAR; PG8_SCHED;
;             PG8_LDA(At, 0, 1); PG8_STAGE(PG8_SB(0, 0), b2, voffB); PG8_STAGE(PG8_SB(0, 1), b2 + hstep, voffB); PG8_STAGE(PG8_SA(0, 0), a2, voffA);
.LBB0_134:
	s_add_u32 s26, s24, 0xfffc0080
	s_addc_u32 s27, s25, -1
	s_add_i32 s51, 0, 0x10000
	s_cmp_eq_u32 s50, 12
	s_cselect_b32 s29, s17, s27
	s_cselect_b32 s28, s23, s26
	v_add_u32_e32 v0, s51, v183
	s_cselect_b32 s27, s15, s49
	s_cselect_b32 s26, s33, s48
	s_add_i32 s54, 0, 0x14000
	ds_read_b128 v[142:145], v0
	ds_read_b128 v[146:149], v0 offset:1024
	ds_read_b128 v[150:153], v0 offset:2048
	ds_read_b128 v[154:157], v0 offset:3072
	v_add_u32_e32 v0, s54, v183
	ds_read_b128 v[158:161], v0
	ds_read_b128 v[162:165], v0 offset:1024
	ds_read_b128 v[166:169], v0 offset:2048
	ds_read_b128 v[170:173], v0 offset:3072
	v_lshl_add_u64 v[208:209], s[24:25], 0, v[138:139]
	s_add_i32 m0, s39, 0xc000
	ds_read_b128 v[174:177], v186
	ds_read_b128 v[178:181], v186 offset:1024
	ds_read_b128 v[188:191], v186 offset:2048
	ds_read_b128 v[192:195], v186 offset:3072
	ds_read_b128 v[196:199], v186 offset:4096
	ds_read_b128 v[200:203], v186 offset:5120
	ds_read_b128 v[204:207], v186 offset:6144
	ds_read_b128 v[218:221], v186 offset:7168
	global_load_lds_dwordx4 v[208:209], off
	v_lshl_add_u64 v[208:209], s[24:25], 0, v[140:141]
	s_add_i32 m0, s39, 0xe000
	s_nop 0
	global_load_lds_dwordx4 v[208:209], off
	s_waitcnt vmcnt(8)
	s_waitcnt lgkmcnt(0)
	s_setprio 1
	s_barrier
	s_waitcnt lgkmcnt(0)
	v_mfma_f32_16x16x32_bf16 v[126:129], v[142:145], v[174:177], v[126:129]
	v_mfma_f32_16x16x32_bf16 v[122:125], v[150:153], v[174:177], v[122:125]
	v_mfma_f32_16x16x32_bf16 v[110:113], v[142:145], v[188:191], v[110:113]
	v_mfma_f32_16x16x32_bf16 v[106:109], v[150:153], v[188:191], v[106:109]
	v_mfma_f32_16x16x32_bf16 v[94:97], v[142:145], v[196:199], v[94:97]
	v_mfma_f32_16x16x32_bf16 v[90:93], v[150:153], v[196:199], v[90:93]
	v_mfma_f32_16x16x32_bf16 v[78:81], v[142:145], v[204:207], v[78:81]
	v_mfma_f32_16x16x32_bf16 v[74:77], v[150:153], v[204:207], v[74:77]
	v_mfma_f32_16x16x32_bf16 v[126:129], v[146:149], v[178:181], v[126:129]
	v_mfma_f32_16x16x32_bf16 v[122:125], v[154:157], v[178:181], v[122:125]
	v_mfma_f32_16x16x32_bf16 v[110:113], v[146:149], v[192:195], v[110:113]
	v_mfma_f32_16x16x32_bf16 v[106:109], v[154:157], v[192:195], v[106:109]
	v_mfma_f32_16x16x32_bf16 v[94:97], v[146:149], v[200:203], v[94:97]
	v_mfma_f32_16x16x32_bf16 v[90:93], v[154:157], v[200:203], v[90:93]
	v_mfma_f32_16x16x32_bf16 v[78:81], v[146:149], v[218:221], v[78:81]
	v_mfma_f32_16x16x32_bf16 v[74:77], v[154:157], v[218:221], v[74:77]
	s_setprio 0
	s_setprio 1
	v_mfma_f32_16x16x32_bf16 v[118:121], v[158:161], v[174:177], v[118:121]
	v_mfma_f32_16x16x32_bf16 v[114:117], v[166:169], v[174:177], v[114:117]
	v_mfma_f32_16x16x32_bf16 v[102:105], v[158:161], v[188:191], v[102:105]
	v_mfma_f32_16x16x32_bf16 v[98:101], v[166:169], v[188:191], v[98:101]
	v_mfma_f32_16x16x32_bf16 v[86:89], v[158:161], v[196:199], v[86:89]
	v_mfma_f32_16x16x32_bf16 v[82:85], v[166:169], v[196:199], v[82:85]
	v_mfma_f32_16x16x32_bf16 v[70:73], v[158:161], v[204:207], v[70:73]
	v_mfma_f32_16x16x32_bf16 v[66:69], v[166:169], v[204:207], v[66:69]
	v_mfma_f32_16x16x32_bf16 v[118:121], v[162:165], v[178:181], v[118:121]
	v_mfma_f32_16x16x32_bf16 v[114:117], v[170:173], v[178:181], v[114:117]
	v_mfma_f32_16x16x32_bf16 v[102:105], v[162:165], v[192:195], v[102:105]
	v_mfma_f32_16x16x32_bf16 v[98:101], v[170:173], v[192:195], v[98:101]
	v_mfma_f32_16x16x32_bf16 v[86:89], v[162:165], v[200:203], v[86:89]
	v_mfma_f32_16x16x32_bf16 v[82:85], v[170:173], v[200:203], v[82:85]
	v_mfma_f32_16x16x32_bf16 v[70:73], v[162:165], v[218:221], v[70:73]
	v_mfma_f32_16x16x32_bf16 v[66:69], v[170:173], v[218:221], v[66:69]
	s_barrier
	s_add_i32 s51, s51, s35
	v_lshl_add_u64 v[208:209], s[26:27], 0, v[134:135]
	s_mov_b32 m0, s51
	ds_read_b128 v[174:177], v186 offset:16384
	ds_read_b128 v[178:181], v186 offset:17408
	ds_read_b128 v[188:191], v186 offset:18432
	ds_read_b128 v[192:195], v186 offset:19456
	ds_read_b128 v[196:199], v186 offset:20480
	ds_read_b128 v[200:203], v186 offset:21504
	ds_read_b128 v[204:207], v186 offset:22528
	ds_read_b128 v[218:221], v186 offset:23552
	s_setprio 0
	global_load_lds_dwordx4 v[208:209], off
	s_add_i32 m0, s51, 0x2000
	s_add_u32 s52, s26, 0x40000
	v_lshl_add_u64 v[210:211], s[26:27], 0, v[130:131]
	s_addc_u32 s53, s27, 0
	s_add_i32 s51, s54, s35
	global_load_lds_dwordx4 v[210:211], off
	v_lshl_add_u64 v[212:213], s[52:53], 0, v[134:135]
	s_mov_b32 m0, s51
	v_lshl_add_u64 v[214:215], s[28:29], 0, v[132:133]
	global_load_lds_dwordx4 v[212:213], off
	v_lshl_add_u64 v[212:213], s[52:53], 0, v[130:131]
	s_add_i32 m0, s51, 0x2000
	s_nop 0
	global_load_lds_dwordx4 v[212:213], off
	v_lshl_add_u64 v[212:213], s[28:29], 0, v[136:137]
	s_mov_b32 m0, s39
	s_nop 0
	global_load_lds_dwordx4 v[212:213], off
	s_mov_b32 m0, s40
	s_nop 0
	global_load_lds_dwordx4 v[214:215], off
	s_waitcnt vmcnt(8)
	s_waitcnt lgkmcnt(0)
	s_setprio 1
	s_barrier
; #define PG8_STAGE(bufoff, gbase, voff) do { _Pragma("unroll") for (int _i = 0; _i < 2; ++_i) \
;         __builtin_amdgcn_global_load_lds((const unsigned*)((const char*)(gbase) + (voff)[_i]), (PG8_LAS unsigned*)(lds + (bufoff) + ldsw + _i * 8192), 16, 0, 0); } while (0)
; #define PG8_LDA(dst, b, h) do { _Pragma("unroll") for (int m = 0; m < 4; ++m) _Pragma("unroll") for (int k = 0; k < 2; ++k) dst[m][k] = *(const PG8_LAS bf16x8*)(lds + PG8_SA(b, h) + aoff + m * 2048 + k * 1024); } while (0)
; #define PG8_LDB(dst, b, h) do { _Pragma("unroll") for (int n = 0; n < 2; ++n) _Pragma("unroll") for (int k = 0; k < 2; ++k) dst[n][k] = *(const PG8_LAS bf16x8*)(lds + PG8_SB(b, h) + boff + n * 2048 + k * 1024); } while (0)
; #define PG8_MMA(ai, bj, At, Bt) do { __builtin_amdgcn_s_setprio(1); _Pragma("unroll") for (int m = 0; m < 4; ++m) _Pragma("unroll") for (int n = 0; n < 2; ++n) _Pragma("unroll") for (int k = 0; k < 2; ++k) \
;         acc[ai][bj][m][n] = __builtin_amdgcn_mfma_f32_16x16x32_bf16(Bt[n][k], At[m][k], acc[ai][bj][m][n], 0, 0, 0); __builtin_amdgcn_s_setprio(0); } while (0)
; #define PG8_WAIT_V(n) asm volatile("s_waitcnt vmcnt(" #n ")" ::: "memory")
; #define PG8_WAIT_L(n) asm volatile("s_waitcnt lgkmcnt(" #n ")" ::: "memory")
; #define PG8_BAR __builtin_amdgcn_s_barrier()
; #define PG8_SCHED __builtin_amdgcn_sched_barrier(0)
; template <class Epi, class Sched, bool ALIGN_EPI = false, bool SP2 = false>
; __device__ __forceinline__ void gemm_phase(PG8_LAS unsigned char* lds, const Gemm g, const Sched& S, const Epi& E, const int wv) {
;     ...
;             PG8_WAIT_V(8); PG8_WAIT_L(0); PG8_BAR; PG8_MMA(1, 0, At, B0); PG8_MMA(1, 1, At, B1); PG8_BAR; PG8_SCHED;
;             PG8_LDB(B0, 1, 0); PG8_LDB(B1, 1, 1); PG8_SCHED; PG8_LDA(At, 1, 0); PG8_STAGE(PG8_SA(0, 1), a2 + hstep, voffA);
;             PG8_WAIT_V(8); PG8_WAIT_L(0); PG8_BAR; PG8_MMA(0, 0, At, B0); PG8_MMA(0, 1, At, B1); PG8_BAR; PG8_SCHED;
	s_waitcnt lgkmcnt(0)
	v_mfma_f32_16x16x32_bf16 v[62:65], v[142:145], v[174:177], v[62:65]
	v_mfma_f32_16x16x32_bf16 v[58:61], v[150:153], v[174:177], v[58:61]
	v_mfma_f32_16x16x32_bf16 v[46:49], v[142:145], v[188:191], v[46:49]
	v_mfma_f32_16x16x32_bf16 v[42:45], v[150:153], v[188:191], v[42:45]
	v_mfma_f32_16x16x32_bf16 v[30:33], v[142:145], v[196:199], v[30:33]
	v_mfma_f32_16x16x32_bf16 v[26:29], v[150:153], v[196:199], v[26:29]
	v_mfma_f32_16x16x32_bf16 v[14:17], v[142:145], v[204:207], v[14:17]
	v_mfma_f32_16x16x32_bf16 v[10:13], v[150:153], v[204:207], v[10:13]
	v_mfma_f32_16x16x32_bf16 v[62:65], v[146:149], v[178:181], v[62:65]
	v_mfma_f32_16x16x32_bf16 v[58:61], v[154:157], v[178:181], v[58:61]
	v_mfma_f32_16x16x32_bf16 v[46:49], v[146:149], v[192:195], v[46:49]
	v_mfma_f32_16x16x32_bf16 v[42:45], v[154:157], v[192:195], v[42:45]
	v_mfma_f32_16x16x32_bf16 v[30:33], v[146:149], v[200:203], v[30:33]
	v_mfma_f32_16x16x32_bf16 v[26:29], v[154:157], v[200:203], v[26:29]
	v_mfma_f32_16x16x32_bf16 v[14:17], v[146:149], v[218:221], v[14:17]
	v_mfma_f32_16x16x32_bf16 v[10:13], v[154:157], v[218:221], v[10:13]
	s_setprio 0
	s_setprio 1
	v_mfma_f32_16x16x32_bf16 v[54:57], v[158:161], v[174:177], v[54:57]
	v_mfma_f32_16x16x32_bf16 v[50:53], v[166:169], v[174:177], v[50:53]
	v_mfma_f32_16x16x32_bf16 v[38:41], v[158:161], v[188:191], v[38:41]
	v_mfma_f32_16x16x32_bf16 v[34:37], v[166:169], v[188:191], v[34:37]
	v_mfma_f32_16x16x32_bf16 v[22:25], v[158:161], v[196:199], v[22:25]
	v_mfma_f32_16x16x32_bf16 v[18:21], v[166:169], v[196:199], v[18:21]
	v_mfma_f32_16x16x32_bf16 v[6:9], v[158:161], v[204:207], v[6:9]
	v_mfma_f32_16x16x32_bf16 v[2:5], v[166:169], v[204:207], v[2:5]
	v_mfma_f32_16x16x32_bf16 v[54:57], v[162:165], v[178:181], v[54:57]
	v_mfma_f32_16x16x32_bf16 v[50:53], v[170:173], v[178:181], v[50:53]
	v_mfma_f32_16x16x32_bf16 v[38:41], v[162:165], v[192:195], v[38:41]
	v_mfma_f32_16x16x32_bf16 v[34:37], v[170:173], v[192:195], v[34:37]
	v_mfma_f32_16x16x32_bf16 v[22:25], v[162:165], v[200:203], v[22:25]
	v_mfma_f32_16x16x32_bf16 v[18:21], v[170:173], v[200:203], v[18:21]
	v_mfma_f32_16x16x32_bf16 v[6:9], v[162:165], v[218:221], v[6:9]
	v_mfma_f32_16x16x32_bf16 v[2:5], v[170:173], v[218:221], v[2:5]
	s_barrier
	s_add_i32 s51, 0, 0x18000
	v_add_u32_e32 v0, s51, v183
	s_add_i32 s52, 0, 0x1c000
	ds_read_b128 v[142:145], v0
	ds_read_b128 v[146:149], v0 offset:1024
	ds_read_b128 v[150:153], v0 offset:2048
	ds_read_b128 v[154:157], v0 offset:3072
	v_add_u32_e32 v0, s52, v183
	ds_read_b128 v[158:161], v0
	ds_read_b128 v[162:165], v0 offset:1024
	ds_read_b128 v[166:169], v0 offset:2048
	ds_read_b128 v[170:173], v0 offset:3072
	s_setprio 0
	s_add_u32 s28, s28, 0x40000
	s_addc_u32 s29, s29, 0
	s_mov_b32 m0, s41
	v_lshl_add_u64 v[216:217], s[28:29], 0, v[136:137]
	ds_read_b128 v[174:177], v186 offset:32768
	ds_read_b128 v[178:181], v186 offset:33792
	ds_read_b128 v[188:191], v186 offset:34816
	ds_read_b128 v[192:195], v186 offset:35840
	ds_read_b128 v[196:199], v186 offset:36864
	ds_read_b128 v[200:203], v186 offset:37888
	ds_read_b128 v[204:207], v186 offset:38912
	ds_read_b128 v[218:221], v186 offset:39936
	global_load_lds_dwordx4 v[216:217], off
	v_lshl_add_u64 v[216:217], s[28:29], 0, v[132:133]
	s_mov_b32 m0, s42
	s_nop 0
	global_load_lds_dwordx4 v[216:217], off
	s_waitcnt vmcnt(8)
	s_waitcnt lgkmcnt(0)
	s_setprio 1
	s_barrier
	s_waitcnt lgkmcnt(0)
	v_mfma_f32_16x16x32_bf16 v[126:129], v[142:145], v[174:177], v[126:129]
	v_mfma_f32_16x16x32_bf16 v[122:125], v[150:153], v[174:177], v[122:125]
	v_mfma_f32_16x16x32_bf16 v[110:113], v[142:145], v[188:191], v[110:113]
	v_mfma_f32_16x16x32_bf16 v[106:109], v[150:153], v[188:191], v[106:109]
	v_mfma_f32_16x16x32_bf16 v[94:97], v[142:145], v[196:199], v[94:97]
	v_mfma_f32_16x16x32_bf16 v[90:93], v[150:153], v[196:199], v[90:93]
	v_mfma_f32_16x16x32_bf16 v[78:81], v[142:145], v[204:207], v[78:81]
	v_mfma_f32_16x16x32_bf16 v[74:77], v[150:153], v[204:207], v[74:77]
	v_mfma_f32_16x16x32_bf16 v[126:129], v[146:149], v[178:181], v[126:129]
	v_mfma_f32_16x16x32_bf16 v[122:125], v[154:157], v[178:181], v[122:125]
	v_mfma_f32_16x16x32_bf16 v[110:113], v[146:149], v[192:195], v[110:113]
	v_mfma_f32_16x16x32_bf16 v[106:109], v[154:157], v[192:195], v[106:109]
	v_mfma_f32_16x16x32_bf16 v[94:97], v[146:149], v[200:203], v[94:97]
	v_mfma_f32_16x16x32_bf16 v[90:93], v[154:157], v[200:203], v[90:93]
	v_mfma_f32_16x16x32_bf16 v[78:81], v[146:149], v[218:221], v[78:81]
	v_mfma_f32_16x16x32_bf16 v[74:77], v[154:157], v[218:221], v[74:77]
	s_setprio 0
	s_setprio 1
	v_mfma_f32_16x16x32_bf16 v[118:121], v[158:161], v[174:177], v[118:121]
	v_mfma_f32_16x16x32_bf16 v[114:117], v[166:169], v[174:177], v[114:117]
	v_mfma_f32_16x16x32_bf16 v[102:105], v[158:161], v[188:191], v[102:105]
	v_mfma_f32_16x16x32_bf16 v[98:101], v[166:169], v[188:191], v[98:101]
	v_mfma_f32_16x16x32_bf16 v[86:89], v[158:161], v[196:199], v[86:89]
	v_mfma_f32_16x16x32_bf16 v[82:85], v[166:169], v[196:199], v[82:85]
	v_mfma_f32_16x16x32_bf16 v[70:73], v[158:161], v[204:207], v[70:73]
	v_mfma_f32_16x16x32_bf16 v[66:69], v[166:169], v[204:207], v[66:69]
	v_mfma_f32_16x16x32_bf16 v[118:121], v[162:165], v[178:181], v[118:121]
	v_mfma_f32_16x16x32_bf16 v[114:117], v[170:173], v[178:181], v[114:117]
	v_mfma_f32_16x16x32_bf16 v[102:105], v[162:165], v[192:195], v[102:105]
	v_mfma_f32_16x16x32_bf16 v[98:101], v[170:173], v[192:195], v[98:101]
	v_mfma_f32_16x16x32_bf16 v[86:89], v[162:165], v[200:203], v[86:89]
	v_mfma_f32_16x16x32_bf16 v[82:85], v[170:173], v[200:203], v[82:85]
	v_mfma_f32_16x16x32_bf16 v[70:73], v[162:165], v[218:221], v[70:73]
	v_mfma_f32_16x16x32_bf16 v[66:69], v[170:173], v[218:221], v[66:69]
	s_barrier
; #define PG8_STAGE(bufoff, gbase, voff) do { _Pragma("unroll") for (int _i = 0; _i < 2; ++_i) \
;         __builtin_amdgcn_global_load_lds((const unsigned*)((const char*)(gbase) + (voff)[_i]), (PG8_LAS unsigned*)(lds + (bufoff) + ldsw + _i * 8192), 16, 0, 0); } while (0)
; #define PG8_LDA(dst, b, h) do { _Pragma("unroll") for (int m = 0; m < 4; ++m) _Pragma("unroll") for (int k = 0; k < 2; ++k) dst[m][k] = *(const PG8_LAS bf16x8*)(lds + PG8_SA(b, h) + aoff + m * 2048 + k * 1024); } while (0)
; #define PG8_MMA(ai, bj, At, Bt) do { __builtin_amdgcn_s_setprio(1); _Pragma("unroll") for (int m = 0; m < 4; ++m) _Pragma("unroll") for (int n = 0; n < 2; ++n) _Pragma("unroll") for (int k = 0; k < 2; ++k) \
;         acc[ai][bj][m][n] = __builtin_amdgcn_mfma_f32_16x16x32_bf16(Bt[n][k], At[m][k], acc[ai][bj][m][n], 0, 0, 0); __builtin_amdgcn_s_setprio(0); } while (0)
; #define PG8_WAIT_V(n) asm volatile("s_waitcnt vmcnt(" #n ")" ::: "memory")
; #define PG8_WAIT_L(n) asm volatile("s_waitcnt lgkmcnt(" #n ")" ::: "memory")
; #define PG8_BAR __builtin_amdgcn_s_barrier()
; #define PG8_SCHED __builtin_amdgcn_sched_barrier(0)
; template <class Epi, class Sched, bool ALIGN_EPI = false, bool SP2 = false>
; __device__ __forceinline__ void gemm_phase(PG8_LAS unsigned char* lds, const Gemm g, const Sched& S, const Epi& E, const int wv) {
;     ...
;             PG8_LDA(At, 1, 1); PG8_STAGE(PG8_SB(1, 0), b3, voffB); PG8_STAGE(PG8_SB(1, 1), b3 + hstep, voffB); PG8_STAGE(PG8_SA(1, 0), a3, voffA);
;             PG8_WAIT_V(8); PG8_WAIT_L(0); PG8_BAR; PG8_MMA(1, 0, At, B0); PG8_MMA(1, 1, At, B1); PG8_BAR; PG8_SCHED;
	s_add_i32 s28, s51, s35
	v_lshl_add_u64 v[208:209], v[208:209], 0, s[2:3]
	s_mov_b32 m0, s28
	ds_read_b128 v[174:177], v186 offset:49152
	ds_read_b128 v[178:181], v186 offset:50176
	ds_read_b128 v[188:191], v186 offset:51200
	ds_read_b128 v[192:195], v186 offset:52224
	ds_read_b128 v[196:199], v186 offset:53248
	ds_read_b128 v[200:203], v186 offset:54272
	ds_read_b128 v[204:207], v186 offset:55296
	ds_read_b128 v[218:221], v186 offset:56320
	s_setprio 0
	global_load_lds_dwordx4 v[208:209], off
	s_add_i32 m0, s28, 0x2000
	s_add_u32 s26, s26, 0x40080
	v_lshl_add_u64 v[208:209], v[210:211], 0, s[2:3]
	s_addc_u32 s27, s27, 0
	s_add_i32 s28, s52, s35
	global_load_lds_dwordx4 v[208:209], off
	v_lshl_add_u64 v[208:209], s[26:27], 0, v[134:135]
	s_mov_b32 m0, s28
	s_nop 0
	global_load_lds_dwordx4 v[208:209], off
	v_lshl_add_u64 v[208:209], s[26:27], 0, v[130:131]
	s_add_i32 m0, s28, 0x2000
	s_nop 0
	global_load_lds_dwordx4 v[208:209], off
	v_lshl_add_u64 v[208:209], v[212:213], 0, s[2:3]
	s_mov_b32 m0, s44
	s_nop 0
	global_load_lds_dwordx4 v[208:209], off
	v_lshl_add_u64 v[208:209], v[214:215], 0, s[2:3]
	s_mov_b32 m0, s45
	s_nop 0
	global_load_lds_dwordx4 v[208:209], off
	s_waitcnt vmcnt(8)
	s_waitcnt lgkmcnt(0)
	s_setprio 1
	s_barrier
	s_waitcnt lgkmcnt(0)
	v_mfma_f32_16x16x32_bf16 v[62:65], v[142:145], v[174:177], v[62:65]
	v_mfma_f32_16x16x32_bf16 v[58:61], v[150:153], v[174:177], v[58:61]
	v_mfma_f32_16x16x32_bf16 v[46:49], v[142:145], v[188:191], v[46:49]
	v_mfma_f32_16x16x32_bf16 v[42:45], v[150:153], v[188:191], v[42:45]
	v_mfma_f32_16x16x32_bf16 v[30:33], v[142:145], v[196:199], v[30:33]
	v_mfma_f32_16x16x32_bf16 v[26:29], v[150:153], v[196:199], v[26:29]
	v_mfma_f32_16x16x32_bf16 v[14:17], v[142:145], v[204:207], v[14:17]
	v_mfma_f32_16x16x32_bf16 v[10:13], v[150:153], v[204:207], v[10:13]
	v_mfma_f32_16x16x32_bf16 v[62:65], v[146:149], v[178:181], v[62:65]
	v_mfma_f32_16x16x32_bf16 v[58:61], v[154:157], v[178:181], v[58:61]
	v_mfma_f32_16x16x32_bf16 v[46:49], v[146:149], v[192:195], v[46:49]
	v_mfma_f32_16x16x32_bf16 v[42:45], v[154:157], v[192:195], v[42:45]
	v_mfma_f32_16x16x32_bf16 v[30:33], v[146:149], v[200:203], v[30:33]
	v_mfma_f32_16x16x32_bf16 v[26:29], v[154:157], v[200:203], v[26:29]
	v_mfma_f32_16x16x32_bf16 v[14:17], v[146:149], v[218:221], v[14:17]
	v_mfma_f32_16x16x32_bf16 v[10:13], v[154:157], v[218:221], v[10:13]
	s_setprio 0
	s_setprio 1
	v_mfma_f32_16x16x32_bf16 v[54:57], v[158:161], v[174:177], v[54:57]
	v_mfma_f32_16x16x32_bf16 v[50:53], v[166:169], v[174:177], v[50:53]
	v_mfma_f32_16x16x32_bf16 v[38:41], v[158:161], v[188:191], v[38:41]
	v_mfma_f32_16x16x32_bf16 v[34:37], v[166:169], v[188:191], v[34:37]
	v_mfma_f32_16x16x32_bf16 v[22:25], v[158:161], v[196:199], v[22:25]
	v_mfma_f32_16x16x32_bf16 v[18:21], v[166:169], v[196:199], v[18:21]
	v_mfma_f32_16x16x32_bf16 v[6:9], v[158:161], v[204:207], v[6:9]
	v_mfma_f32_16x16x32_bf16 v[2:5], v[166:169], v[204:207], v[2:5]
	v_mfma_f32_16x16x32_bf16 v[54:57], v[162:165], v[178:181], v[54:57]
	v_mfma_f32_16x16x32_bf16 v[50:53], v[170:173], v[178:181], v[50:53]
	v_mfma_f32_16x16x32_bf16 v[38:41], v[162:165], v[192:195], v[38:41]
	v_mfma_f32_16x16x32_bf16 v[34:37], v[170:173], v[192:195], v[34:37]
	v_mfma_f32_16x16x32_bf16 v[22:25], v[162:165], v[200:203], v[22:25]
	v_mfma_f32_16x16x32_bf16 v[18:21], v[170:173], v[200:203], v[18:21]
	v_mfma_f32_16x16x32_bf16 v[6:9], v[162:165], v[218:221], v[6:9]
	v_mfma_f32_16x16x32_bf16 v[2:5], v[170:173], v[218:221], v[2:5]
	s_barrier
	s_setprio 0
	s_add_i32 s50, s50, 2
	s_add_u32 s24, s24, 0x100
	s_addc_u32 s25, s25, 0
	s_add_u32 s48, s48, 0x100
	s_addc_u32 s49, s49, 0
	s_cmp_gt_u32 s50, 13
	s_cbranch_scc0 .LBB0_134
	s_and_b64 vcc, exec, s[10:11]
	s_cbranch_vccz .LBB0_137
	s_barrier

; #define PG8_STAGE(bufoff, gbase, voff) do { _Pragma("unroll") for (int _i = 0; _i < 2; ++_i) \
;         __builtin_amdgcn_global_load_lds((const unsigned*)((const char*)(gbase) + (voff)[_i]), (PG8_LAS unsigned*)(lds + (bufoff) + ldsw + _i * 8192), 16, 0, 0); } while (0)
; #define PG8_LDA(dst, b, h) do { _Pragma("unroll") for (int m = 0; m < 4; ++m) _Pragma("unroll") for (int k = 0; k < 2; ++k) dst[m][k] = *(const PG8_LAS bf16x8*)(lds + PG8_SA(b, h) + aoff + m * 2048 + k * 1024); } while (0)
; #define PG8_LDB(dst, b, h) do { _Pragma("unroll") for (int n = 0; n < 2; ++n) _Pragma("unroll") for (int k = 0; k < 2; ++k) dst[n][k] = *(const PG8_LAS bf16x8*)(lds + PG8_SB(b, h) + boff + n * 2048 + k * 1024); } while (0)
; #define PG8_MMA(ai, bj, At, Bt) do { __builtin_amdgcn_s_setprio(1); _Pragma("unroll") for (int m = 0; m < 4; ++m) _Pragma("unroll") for (int n = 0; n < 2; ++n) _Pragma("unroll") for (int k = 0; k < 2; ++k) \
;         acc[ai][bj][m][n] = __builtin_amdgcn_mfma_f32_16x16x32_bf16(Bt[n][k], At[m][k], acc[ai][bj][m][n], 0, 0, 0); __builtin_amdgcn_s_setprio(0); } while (0)
; #define PG8_WAIT_V(n) asm volatile("s_waitcnt vmcnt(" #n ")" ::: "memory")
; #define PG8_WAIT_L(n) asm volatile("s_waitcnt lgkmcnt(" #n ")" ::: "memory")
; #define PG8_BAR __builtin_amdgcn_s_barrier()
; #define PG8_SCHED __builtin_amdgcn_sched_barrier(0)
; template <class Epi, class Sched, bool ALIGN_EPI = false, bool SP2 = false>
; __device__ __forceinline__ void gemm_phase(PG8_LAS unsigned char* lds, const Gemm g, const Sched& S, const Epi& E, const int wv) {
;     ...
;             const bool last = (t == nt - 2);
;             const char* a1 = cA + (size_t)(t + 1) * kstep;
;             const char* a2 = last ? nA : cA + (size_t)(t + 2) * kstep; const char* b2 = last ? nB : cB + (size_t)(t + 2) * kstep;
;             const char* a3 = a2 + kstep; const char* b3 = b2 + kstep;
;             if (last && has_next) S.a_ready(nxt);
;             if constexpr (SP2) {
;             PG8_LDB(B0, 0, 0); PG8_LDB(B1, 0, 1); PG8_SCHED; PG8_LDA(At, 0, 0); PG8_STAGE(PG8_SA(1, 1), a1 + hstep, voffA);
;             PG8_WAIT_V(8); PG8_WAIT_L(0); PG8_BAR; PG8_MMA(0, 0, At, B0); PG8_MMA(0, 1, At, B1); PG8_BAR; PG8_SCHED;
;             PG8_LDA(At, 0, 1); PG8_STAGE(PG8_SB(0, 0), b2, voffB); PG8_STAGE(PG8_SB(0, 1), b2 + hstep, voffB); PG8_STAGE(PG8_SA(0, 0), a2, voffA);
.LBB0_156:
	s_add_u32 s20, s18, 0xfffc0080
	s_addc_u32 s21, s19, -1
	s_add_i32 s45, 0, 0x10000
	s_cmp_eq_u32 s44, 12
	s_cselect_b32 s23, s11, s21
	s_cselect_b32 s22, s40, s20
	v_add_u32_e32 v152, s45, v155
	s_cselect_b32 s21, s9, s43
	s_cselect_b32 s20, s41, s42
	s_add_i32 s48, 0, 0x14000
	ds_read_b128 v[140:143], v152
	ds_read_b128 v[144:147], v152 offset:1024
	ds_read_b128 v[148:151], v152 offset:2048
	ds_read_b128 v[158:161], v152 offset:3072
	v_add_u32_e32 v152, s48, v155
	ds_read_b128 v[162:165], v152
	ds_read_b128 v[166:169], v152 offset:1024
	ds_read_b128 v[170:173], v152 offset:2048
	ds_read_b128 v[174:177], v152 offset:3072
	v_lshl_add_u64 v[152:153], s[18:19], 0, v[136:137]
	s_add_i32 m0, s17, 0xc000
	ds_read_b128 v[178:181], v157
	ds_read_b128 v[182:185], v157 offset:1024
	ds_read_b128 v[186:189], v157 offset:2048
	ds_read_b128 v[190:193], v157 offset:3072
	ds_read_b128 v[194:197], v157 offset:4096
	ds_read_b128 v[198:201], v157 offset:5120
	ds_read_b128 v[202:205], v157 offset:6144
	ds_read_b128 v[206:209], v157 offset:7168
	global_load_lds_dwordx4 v[152:153], off
	v_lshl_add_u64 v[152:153], s[18:19], 0, v[138:139]
	s_add_i32 m0, s17, 0xe000
	s_nop 0
	global_load_lds_dwordx4 v[152:153], off
	s_waitcnt vmcnt(8)
	s_waitcnt lgkmcnt(0)
	s_setprio 1
	s_barrier
	s_waitcnt lgkmcnt(0)
	v_mfma_f32_16x16x32_bf16 v[126:129], v[140:143], v[178:181], v[126:129]
	v_mfma_f32_16x16x32_bf16 v[122:125], v[148:151], v[178:181], v[122:125]
	v_mfma_f32_16x16x32_bf16 v[118:121], v[140:143], v[186:189], v[118:121]
	v_mfma_f32_16x16x32_bf16 v[114:117], v[148:151], v[186:189], v[114:117]
	v_mfma_f32_16x16x32_bf16 v[98:101], v[140:143], v[194:197], v[98:101]
	v_mfma_f32_16x16x32_bf16 v[90:93], v[148:151], v[194:197], v[90:93]
	v_mfma_f32_16x16x32_bf16 v[78:81], v[140:143], v[202:205], v[78:81]
	v_mfma_f32_16x16x32_bf16 v[74:77], v[148:151], v[202:205], v[74:77]
	v_mfma_f32_16x16x32_bf16 v[126:129], v[144:147], v[182:185], v[126:129]
	v_mfma_f32_16x16x32_bf16 v[122:125], v[158:161], v[182:185], v[122:125]
	v_mfma_f32_16x16x32_bf16 v[118:121], v[144:147], v[190:193], v[118:121]
	v_mfma_f32_16x16x32_bf16 v[114:117], v[158:161], v[190:193], v[114:117]
	v_mfma_f32_16x16x32_bf16 v[98:101], v[144:147], v[198:201], v[98:101]
	v_mfma_f32_16x16x32_bf16 v[90:93], v[158:161], v[198:201], v[90:93]
	v_mfma_f32_16x16x32_bf16 v[78:81], v[144:147], v[206:209], v[78:81]
	v_mfma_f32_16x16x32_bf16 v[74:77], v[158:161], v[206:209], v[74:77]
	s_setprio 0
	s_setprio 1
	v_mfma_f32_16x16x32_bf16 v[110:113], v[162:165], v[178:181], v[110:113]
	v_mfma_f32_16x16x32_bf16 v[106:109], v[170:173], v[178:181], v[106:109]
	v_mfma_f32_16x16x32_bf16 v[102:105], v[162:165], v[186:189], v[102:105]
	v_mfma_f32_16x16x32_bf16 v[94:97], v[170:173], v[186:189], v[94:97]
	v_mfma_f32_16x16x32_bf16 v[86:89], v[162:165], v[194:197], v[86:89]
	v_mfma_f32_16x16x32_bf16 v[82:85], v[170:173], v[194:197], v[82:85]
	v_mfma_f32_16x16x32_bf16 v[70:73], v[162:165], v[202:205], v[70:73]
	v_mfma_f32_16x16x32_bf16 v[66:69], v[170:173], v[202:205], v[66:69]
	v_mfma_f32_16x16x32_bf16 v[110:113], v[166:169], v[182:185], v[110:113]
	v_mfma_f32_16x16x32_bf16 v[106:109], v[174:177], v[182:185], v[106:109]
	v_mfma_f32_16x16x32_bf16 v[102:105], v[166:169], v[190:193], v[102:105]
	v_mfma_f32_16x16x32_bf16 v[94:97], v[174:177], v[190:193], v[94:97]
	v_mfma_f32_16x16x32_bf16 v[86:89], v[166:169], v[198:201], v[86:89]
	v_mfma_f32_16x16x32_bf16 v[82:85], v[174:177], v[198:201], v[82:85]
	v_mfma_f32_16x16x32_bf16 v[70:73], v[166:169], v[206:209], v[70:73]
	v_mfma_f32_16x16x32_bf16 v[66:69], v[174:177], v[206:209], v[66:69]
	s_barrier
	s_add_i32 s45, s45, s24
	v_lshl_add_u64 v[152:153], s[20:21], 0, v[0:1]
	s_mov_b32 m0, s45
	ds_read_b128 v[178:181], v157 offset:16384
	ds_read_b128 v[182:185], v157 offset:17408
	ds_read_b128 v[186:189], v157 offset:18432
	ds_read_b128 v[190:193], v157 offset:19456
	ds_read_b128 v[194:197], v157 offset:20480
	ds_read_b128 v[198:201], v157 offset:21504
	ds_read_b128 v[202:205], v157 offset:22528
	ds_read_b128 v[206:209], v157 offset:23552
	s_setprio 0
	global_load_lds_dwordx4 v[152:153], off
	s_add_i32 m0, s45, 0x2000
	s_add_u32 s46, s20, 0x40000
	v_lshl_add_u64 v[210:211], s[20:21], 0, v[130:131]
	s_addc_u32 s47, s21, 0
	s_add_i32 s45, s48, s24
	global_load_lds_dwordx4 v[210:211], off
	v_lshl_add_u64 v[212:213], s[46:47], 0, v[0:1]
	s_mov_b32 m0, s45
	v_lshl_add_u64 v[214:215], s[22:23], 0, v[132:133]
	global_load_lds_dwordx4 v[212:213], off
	v_lshl_add_u64 v[212:213], s[46:47], 0, v[130:131]
	s_add_i32 m0, s45, 0x2000
	s_nop 0
	global_load_lds_dwordx4 v[212:213], off
	v_lshl_add_u64 v[212:213], s[22:23], 0, v[134:135]
	s_mov_b32 m0, s17
	s_nop 0
	global_load_lds_dwordx4 v[212:213], off
	s_mov_b32 m0, s26
	s_nop 0
	global_load_lds_dwordx4 v[214:215], off
	s_waitcnt vmcnt(8)
	s_waitcnt lgkmcnt(0)
	s_setprio 1
	s_barrier
; #define PG8_STAGE(bufoff, gbase, voff) do { _Pragma("unroll") for (int _i = 0; _i < 2; ++_i) \
;         __builtin_amdgcn_global_load_lds((const unsigned*)((const char*)(gbase) + (voff)[_i]), (PG8_LAS unsigned*)(lds + (bufoff) + ldsw + _i * 8192), 16, 0, 0); } while (0)
; #define PG8_LDA(dst, b, h) do { _Pragma("unroll") for (int m = 0; m < 4; ++m) _Pragma("unroll") for (int k = 0; k < 2; ++k) dst[m][k] = *(const PG8_LAS bf16x8*)(lds + PG8_SA(b, h) + aoff + m * 2048 + k * 1024); } while (0)
; #define PG8_LDB(dst, b, h) do { _Pragma("unroll") for (int n = 0; n < 2; ++n) _Pragma("unroll") for (int k = 0; k < 2; ++k) dst[n][k] = *(const PG8_LAS bf16x8*)(lds + PG8_SB(b, h) + boff + n * 2048 + k * 1024); } while (0)
; #define PG8_MMA(ai, bj, At, Bt) do { __builtin_amdgcn_s_setprio(1); _Pragma("unroll") for (int m = 0; m < 4; ++m) _Pragma("unroll") for (int n = 0; n < 2; ++n) _Pragma("unroll") for (int k = 0; k < 2; ++k) \
;         acc[ai][bj][m][n] = __builtin_amdgcn_mfma_f32_16x16x32_bf16(Bt[n][k], At[m][k], acc[ai][bj][m][n], 0, 0, 0); __builtin_amdgcn_s_setprio(0); } while (0)
; #define PG8_WAIT_V(n) asm volatile("s_waitcnt vmcnt(" #n ")" ::: "memory")
; #define PG8_WAIT_L(n) asm volatile("s_waitcnt lgkmcnt(" #n ")" ::: "memory")
; #define PG8_BAR __builtin_amdgcn_s_barrier()
; #define PG8_SCHED __builtin_amdgcn_sched_barrier(0)
; template <class Epi, class Sched, bool ALIGN_EPI = false, bool SP2 = false>
; __device__ __forceinline__ void gemm_phase(PG8_LAS unsigned char* lds, const Gemm g, const Sched& S, const Epi& E, const int wv) {
;     ...
;             PG8_WAIT_V(8); PG8_WAIT_L(0); PG8_BAR; PG8_MMA(1, 0, At, B0); PG8_MMA(1, 1, At, B1); PG8_BAR; PG8_SCHED;
;             PG8_LDB(B0, 1, 0); PG8_LDB(B1, 1, 1); PG8_SCHED; PG8_LDA(At, 1, 0); PG8_STAGE(PG8_SA(0, 1), a2 + hstep, voffA);
;             PG8_WAIT_V(8); PG8_WAIT_L(0); PG8_BAR; PG8_MMA(0, 0, At, B0); PG8_MMA(0, 1, At, B1); PG8_BAR; PG8_SCHED;
	s_waitcnt lgkmcnt(0)
	v_mfma_f32_16x16x32_bf16 v[62:65], v[140:143], v[178:181], v[62:65]
	v_mfma_f32_16x16x32_bf16 v[58:61], v[148:151], v[178:181], v[58:61]
	v_mfma_f32_16x16x32_bf16 v[46:49], v[140:143], v[186:189], v[46:49]
	v_mfma_f32_16x16x32_bf16 v[42:45], v[148:151], v[186:189], v[42:45]
	v_mfma_f32_16x16x32_bf16 v[30:33], v[140:143], v[194:197], v[30:33]
	v_mfma_f32_16x16x32_bf16 v[26:29], v[148:151], v[194:197], v[26:29]
	v_mfma_f32_16x16x32_bf16 v[14:17], v[140:143], v[202:205], v[14:17]
	v_mfma_f32_16x16x32_bf16 v[10:13], v[148:151], v[202:205], v[10:13]
	v_mfma_f32_16x16x32_bf16 v[62:65], v[144:147], v[182:185], v[62:65]
	v_mfma_f32_16x16x32_bf16 v[58:61], v[158:161], v[182:185], v[58:61]
	v_mfma_f32_16x16x32_bf16 v[46:49], v[144:147], v[190:193], v[46:49]
	v_mfma_f32_16x16x32_bf16 v[42:45], v[158:161], v[190:193], v[42:45]
	v_mfma_f32_16x16x32_bf16 v[30:33], v[144:147], v[198:201], v[30:33]
	v_mfma_f32_16x16x32_bf16 v[26:29], v[158:161], v[198:201], v[26:29]
	v_mfma_f32_16x16x32_bf16 v[14:17], v[144:147], v[206:209], v[14:17]
	v_mfma_f32_16x16x32_bf16 v[10:13], v[158:161], v[206:209], v[10:13]
	s_setprio 0
	s_setprio 1
	v_mfma_f32_16x16x32_bf16 v[54:57], v[162:165], v[178:181], v[54:57]
	v_mfma_f32_16x16x32_bf16 v[50:53], v[170:173], v[178:181], v[50:53]
	v_mfma_f32_16x16x32_bf16 v[38:41], v[162:165], v[186:189], v[38:41]
	v_mfma_f32_16x16x32_bf16 v[34:37], v[170:173], v[186:189], v[34:37]
	v_mfma_f32_16x16x32_bf16 v[22:25], v[162:165], v[194:197], v[22:25]
	v_mfma_f32_16x16x32_bf16 v[18:21], v[170:173], v[194:197], v[18:21]
	v_mfma_f32_16x16x32_bf16 v[6:9], v[162:165], v[202:205], v[6:9]
	v_mfma_f32_16x16x32_bf16 v[2:5], v[170:173], v[202:205], v[2:5]
	v_mfma_f32_16x16x32_bf16 v[54:57], v[166:169], v[182:185], v[54:57]
	v_mfma_f32_16x16x32_bf16 v[50:53], v[174:177], v[182:185], v[50:53]
	v_mfma_f32_16x16x32_bf16 v[38:41], v[166:169], v[190:193], v[38:41]
	v_mfma_f32_16x16x32_bf16 v[34:37], v[174:177], v[190:193], v[34:37]
	v_mfma_f32_16x16x32_bf16 v[22:25], v[166:169], v[198:201], v[22:25]
	v_mfma_f32_16x16x32_bf16 v[18:21], v[174:177], v[198:201], v[18:21]
	v_mfma_f32_16x16x32_bf16 v[6:9], v[166:169], v[206:209], v[6:9]
	v_mfma_f32_16x16x32_bf16 v[2:5], v[174:177], v[206:209], v[2:5]
	s_barrier
	s_add_i32 s45, 0, 0x18000
	s_add_i32 s46, 0, 0x1c000
	v_add_u32_e32 v158, s45, v155
	v_add_u32_e32 v174, s46, v155
	ds_read_b128 v[140:143], v158
	ds_read_b128 v[144:147], v158 offset:1024
	ds_read_b128 v[148:151], v158 offset:2048
	ds_read_b128 v[158:161], v158 offset:3072
	ds_read_b128 v[162:165], v174
	ds_read_b128 v[166:169], v174 offset:1024
	ds_read_b128 v[170:173], v174 offset:2048
	ds_read_b128 v[174:177], v174 offset:3072
	s_setprio 0
	s_add_u32 s22, s22, 0x40000
	s_addc_u32 s23, s23, 0
	s_mov_b32 m0, s27
	v_lshl_add_u64 v[216:217], s[22:23], 0, v[134:135]
	ds_read_b128 v[178:181], v157 offset:32768
	ds_read_b128 v[182:185], v157 offset:33792
	ds_read_b128 v[186:189], v157 offset:34816
	ds_read_b128 v[190:193], v157 offset:35840
	ds_read_b128 v[194:197], v157 offset:36864
	ds_read_b128 v[198:201], v157 offset:37888
	ds_read_b128 v[202:205], v157 offset:38912
	ds_read_b128 v[206:209], v157 offset:39936
	global_load_lds_dwordx4 v[216:217], off
	v_lshl_add_u64 v[216:217], s[22:23], 0, v[132:133]
	s_mov_b32 m0, s28
	s_nop 0
	global_load_lds_dwordx4 v[216:217], off
	s_waitcnt vmcnt(8)
	s_waitcnt lgkmcnt(0)
	s_setprio 1
	s_barrier
	s_waitcnt lgkmcnt(0)
	v_mfma_f32_16x16x32_bf16 v[126:129], v[140:143], v[178:181], v[126:129]
	v_mfma_f32_16x16x32_bf16 v[122:125], v[148:151], v[178:181], v[122:125]
	v_mfma_f32_16x16x32_bf16 v[118:121], v[140:143], v[186:189], v[118:121]
	v_mfma_f32_16x16x32_bf16 v[114:117], v[148:151], v[186:189], v[114:117]
	v_mfma_f32_16x16x32_bf16 v[98:101], v[140:143], v[194:197], v[98:101]
	v_mfma_f32_16x16x32_bf16 v[90:93], v[148:151], v[194:197], v[90:93]
	v_mfma_f32_16x16x32_bf16 v[78:81], v[140:143], v[202:205], v[78:81]
	v_mfma_f32_16x16x32_bf16 v[74:77], v[148:151], v[202:205], v[74:77]
	v_mfma_f32_16x16x32_bf16 v[126:129], v[144:147], v[182:185], v[126:129]
	v_mfma_f32_16x16x32_bf16 v[122:125], v[158:161], v[182:185], v[122:125]
	v_mfma_f32_16x16x32_bf16 v[118:121], v[144:147], v[190:193], v[118:121]
	v_mfma_f32_16x16x32_bf16 v[114:117], v[158:161], v[190:193], v[114:117]
	v_mfma_f32_16x16x32_bf16 v[98:101], v[144:147], v[198:201], v[98:101]
	v_mfma_f32_16x16x32_bf16 v[90:93], v[158:161], v[198:201], v[90:93]
	v_mfma_f32_16x16x32_bf16 v[78:81], v[144:147], v[206:209], v[78:81]
	v_mfma_f32_16x16x32_bf16 v[74:77], v[158:161], v[206:209], v[74:77]
	s_setprio 0
	s_setprio 1
	v_mfma_f32_16x16x32_bf16 v[110:113], v[162:165], v[178:181], v[110:113]
	v_mfma_f32_16x16x32_bf16 v[106:109], v[170:173], v[178:181], v[106:109]
	v_mfma_f32_16x16x32_bf16 v[102:105], v[162:165], v[186:189], v[102:105]
	v_mfma_f32_16x16x32_bf16 v[94:97], v[170:173], v[186:189], v[94:97]
	v_mfma_f32_16x16x32_bf16 v[86:89], v[162:165], v[194:197], v[86:89]
	v_mfma_f32_16x16x32_bf16 v[82:85], v[170:173], v[194:197], v[82:85]
	v_mfma_f32_16x16x32_bf16 v[70:73], v[162:165], v[202:205], v[70:73]
	v_mfma_f32_16x16x32_bf16 v[66:69], v[170:173], v[202:205], v[66:69]
	v_mfma_f32_16x16x32_bf16 v[110:113], v[166:169], v[182:185], v[110:113]
	v_mfma_f32_16x16x32_bf16 v[106:109], v[174:177], v[182:185], v[106:109]
	v_mfma_f32_16x16x32_bf16 v[102:105], v[166:169], v[190:193], v[102:105]
	v_mfma_f32_16x16x32_bf16 v[94:97], v[174:177], v[190:193], v[94:97]
	v_mfma_f32_16x16x32_bf16 v[86:89], v[166:169], v[198:201], v[86:89]
	v_mfma_f32_16x16x32_bf16 v[82:85], v[174:177], v[198:201], v[82:85]
	v_mfma_f32_16x16x32_bf16 v[70:73], v[166:169], v[206:209], v[70:73]
	v_mfma_f32_16x16x32_bf16 v[66:69], v[174:177], v[206:209], v[66:69]
	s_barrier
; #define PG8_STAGE(bufoff, gbase, voff) do { _Pragma("unroll") for (int _i = 0; _i < 2; ++_i) \
;         __builtin_amdgcn_global_load_lds((const unsigned*)((const char*)(gbase) + (voff)[_i]), (PG8_LAS unsigned*)(lds + (bufoff) + ldsw + _i * 8192), 16, 0, 0); } while (0)
; #define PG8_LDA(dst, b, h) do { _Pragma("unroll") for (int m = 0; m < 4; ++m) _Pragma("unroll") for (int k = 0; k < 2; ++k) dst[m][k] = *(const PG8_LAS bf16x8*)(lds + PG8_SA(b, h) + aoff + m * 2048 + k * 1024); } while (0)
; #define PG8_MMA(ai, bj, At, Bt) do { __builtin_amdgcn_s_setprio(1); _Pragma("unroll") for (int m = 0; m < 4; ++m) _Pragma("unroll") for (int n = 0; n < 2; ++n) _Pragma("unroll") for (int k = 0; k < 2; ++k) \
;         acc[ai][bj][m][n] = __builtin_amdgcn_mfma_f32_16x16x32_bf16(Bt[n][k], At[m][k], acc[ai][bj][m][n], 0, 0, 0); __builtin_amdgcn_s_setprio(0); } while (0)
; #define PG8_WAIT_V(n) asm volatile("s_waitcnt vmcnt(" #n ")" ::: "memory")
; #define PG8_WAIT_L(n) asm volatile("s_waitcnt lgkmcnt(" #n ")" ::: "memory")
; #define PG8_BAR __builtin_amdgcn_s_barrier()
; #define PG8_SCHED __builtin_amdgcn_sched_barrier(0)
; template <class Epi, class Sched, bool ALIGN_EPI = false, bool SP2 = false>
; __device__ __forceinline__ void gemm_phase(PG8_LAS unsigned char* lds, const Gemm g, const Sched& S, const Epi& E, const int wv) {
;     ...
;             PG8_LDA(At, 1, 1); PG8_STAGE(PG8_SB(1, 0), b3, voffB); PG8_STAGE(PG8_SB(1, 1), b3 + hstep, voffB); PG8_STAGE(PG8_SA(1, 0), a3, voffA);
;             PG8_WAIT_V(8); PG8_WAIT_L(0); PG8_BAR; PG8_MMA(1, 0, At, B0); PG8_MMA(1, 1, At, B1); PG8_BAR; PG8_SCHED;
	s_add_i32 s22, s45, s24
	v_lshl_add_u64 v[152:153], v[152:153], 0, s[2:3]
	s_mov_b32 m0, s22
	ds_read_b128 v[178:181], v157 offset:49152
	ds_read_b128 v[182:185], v157 offset:50176
	ds_read_b128 v[186:189], v157 offset:51200
	ds_read_b128 v[190:193], v157 offset:52224
	ds_read_b128 v[194:197], v157 offset:53248
	ds_read_b128 v[198:201], v157 offset:54272
	ds_read_b128 v[202:205], v157 offset:55296
	ds_read_b128 v[206:209], v157 offset:56320
	s_setprio 0
	global_load_lds_dwordx4 v[152:153], off
	s_add_i32 m0, s22, 0x2000
	s_add_u32 s20, s20, 0x40080
	v_lshl_add_u64 v[152:153], v[210:211], 0, s[2:3]
	s_addc_u32 s21, s21, 0
	s_add_i32 s22, s46, s24
	global_load_lds_dwordx4 v[152:153], off
	v_lshl_add_u64 v[152:153], s[20:21], 0, v[0:1]
	s_mov_b32 m0, s22
	s_nop 0
	global_load_lds_dwordx4 v[152:153], off
	v_lshl_add_u64 v[152:153], s[20:21], 0, v[130:131]
	s_add_i32 m0, s22, 0x2000
	s_nop 0
	global_load_lds_dwordx4 v[152:153], off
	v_lshl_add_u64 v[152:153], v[212:213], 0, s[2:3]
	s_mov_b32 m0, s33
	s_nop 0
	global_load_lds_dwordx4 v[152:153], off
	v_lshl_add_u64 v[152:153], v[214:215], 0, s[2:3]
	s_mov_b32 m0, s35
	s_nop 0
	global_load_lds_dwordx4 v[152:153], off
	s_waitcnt vmcnt(8)
	s_waitcnt lgkmcnt(0)
	s_setprio 1
	s_barrier
	s_waitcnt lgkmcnt(0)
	v_mfma_f32_16x16x32_bf16 v[62:65], v[140:143], v[178:181], v[62:65]
	v_mfma_f32_16x16x32_bf16 v[58:61], v[148:151], v[178:181], v[58:61]
	v_mfma_f32_16x16x32_bf16 v[46:49], v[140:143], v[186:189], v[46:49]
	v_mfma_f32_16x16x32_bf16 v[42:45], v[148:151], v[186:189], v[42:45]
	v_mfma_f32_16x16x32_bf16 v[30:33], v[140:143], v[194:197], v[30:33]
	v_mfma_f32_16x16x32_bf16 v[26:29], v[148:151], v[194:197], v[26:29]
	v_mfma_f32_16x16x32_bf16 v[14:17], v[140:143], v[202:205], v[14:17]
	v_mfma_f32_16x16x32_bf16 v[10:13], v[148:151], v[202:205], v[10:13]
	v_mfma_f32_16x16x32_bf16 v[62:65], v[144:147], v[182:185], v[62:65]
	v_mfma_f32_16x16x32_bf16 v[58:61], v[158:161], v[182:185], v[58:61]
	v_mfma_f32_16x16x32_bf16 v[46:49], v[144:147], v[190:193], v[46:49]
	v_mfma_f32_16x16x32_bf16 v[42:45], v[158:161], v[190:193], v[42:45]
	v_mfma_f32_16x16x32_bf16 v[30:33], v[144:147], v[198:201], v[30:33]
	v_mfma_f32_16x16x32_bf16 v[26:29], v[158:161], v[198:201], v[26:29]
	v_mfma_f32_16x16x32_bf16 v[14:17], v[144:147], v[206:209], v[14:17]
	v_mfma_f32_16x16x32_bf16 v[10:13], v[158:161], v[206:209], v[10:13]
	s_setprio 0
	s_setprio 1
	v_mfma_f32_16x16x32_bf16 v[54:57], v[162:165], v[178:181], v[54:57]
	v_mfma_f32_16x16x32_bf16 v[50:53], v[170:173], v[178:181], v[50:53]
	v_mfma_f32_16x16x32_bf16 v[38:41], v[162:165], v[186:189], v[38:41]
	v_mfma_f32_16x16x32_bf16 v[34:37], v[170:173], v[186:189], v[34:37]
	v_mfma_f32_16x16x32_bf16 v[22:25], v[162:165], v[194:197], v[22:25]
	v_mfma_f32_16x16x32_bf16 v[18:21], v[170:173], v[194:197], v[18:21]
	v_mfma_f32_16x16x32_bf16 v[6:9], v[162:165], v[202:205], v[6:9]
	v_mfma_f32_16x16x32_bf16 v[2:5], v[170:173], v[202:205], v[2:5]
	v_mfma_f32_16x16x32_bf16 v[54:57], v[166:169], v[182:185], v[54:57]
	v_mfma_f32_16x16x32_bf16 v[50:53], v[174:177], v[182:185], v[50:53]
	v_mfma_f32_16x16x32_bf16 v[38:41], v[166:169], v[190:193], v[38:41]
	v_mfma_f32_16x16x32_bf16 v[34:37], v[174:177], v[190:193], v[34:37]
	v_mfma_f32_16x16x32_bf16 v[22:25], v[166:169], v[198:201], v[22:25]
	v_mfma_f32_16x16x32_bf16 v[18:21], v[174:177], v[198:201], v[18:21]
	v_mfma_f32_16x16x32_bf16 v[6:9], v[166:169], v[206:209], v[6:9]
	v_mfma_f32_16x16x32_bf16 v[2:5], v[174:177], v[206:209], v[2:5]
	s_barrier
	s_setprio 0
	s_add_i32 s44, s44, 2
	s_add_u32 s18, s18, 0x100
	s_addc_u32 s19, s19, 0
	s_add_u32 s42, s42, 0x100
	s_addc_u32 s43, s43, 0
	s_cmp_gt_u32 s44, 13
	s_cbranch_scc0 .LBB0_156
	s_and_b64 vcc, exec, s[6:7]
	s_cbranch_vccz .LBB0_159
	s_barrier

; #define PG8_STAGE(bufoff, gbase, voff) do { _Pragma("unroll") for (int _i = 0; _i < 2; ++_i) \
;         __builtin_amdgcn_global_load_lds((const unsigned*)((const char*)(gbase) + (voff)[_i]), (PG8_LAS unsigned*)(lds + (bufoff) + ldsw + _i * 8192), 16, 0, 0); } while (0)
; #define PG8_LDA(dst, b, h) do { _Pragma("unroll") for (int m = 0; m < 4; ++m) _Pragma("unroll") for (int k = 0; k < 2; ++k) dst[m][k] = *(const PG8_LAS bf16x8*)(lds + PG8_SA(b, h) + aoff + m * 2048 + k * 1024); } while (0)
; #define PG8_LDB(dst, b, h) do { _Pragma("unroll") for (int n = 0; n < 2; ++n) _Pragma("unroll") for (int k = 0; k < 2; ++k) dst[n][k] = *(const PG8_LAS bf16x8*)(lds + PG8_SB(b, h) + boff + n * 2048 + k * 1024); } while (0)
; #define PG8_MMA(ai, bj, At, Bt) do { __builtin_amdgcn_s_setprio(1); _Pragma("unroll") for (int m = 0; m < 4; ++m) _Pragma("unroll") for (int n = 0; n < 2; ++n) _Pragma("unroll") for (int k = 0; k < 2; ++k) \
;         acc[ai][bj][m][n] = __builtin_amdgcn_mfma_f32_16x16x32_bf16(Bt[n][k], At[m][k], acc[ai][bj][m][n], 0, 0, 0); __builtin_amdgcn_s_setprio(0); } while (0)
; #define PG8_WAIT_V(n) asm volatile("s_waitcnt vmcnt(" #n ")" ::: "memory")
; #define PG8_WAIT_L(n) asm volatile("s_waitcnt lgkmcnt(" #n ")" ::: "memory")
; #define PG8_BAR __builtin_amdgcn_s_barrier()
; #define PG8_SCHED __builtin_amdgcn_sched_barrier(0)
; template <class Epi, class Sched, bool ALIGN_EPI = false, bool SP2 = false>
; __device__ __forceinline__ void gemm_phase(PG8_LAS unsigned char* lds, const Gemm g, const Sched& S, const Epi& E, const int wv) {
;     ...
;             const bool last = (t == nt - 2);
;             const char* a1 = cA + (size_t)(t + 1) * kstep;
;             const char* a2 = last ? nA : cA + (size_t)(t + 2) * kstep; const char* b2 = last ? nB : cB + (size_t)(t + 2) * kstep;
;             const char* a3 = a2 + kstep; const char* b3 = b2 + kstep;
;             if (last && has_next) S.a_ready(nxt);
;             if constexpr (SP2) {
;             PG8_LDB(B0, 0, 0); PG8_LDB(B1, 0, 1); PG8_SCHED; PG8_LDA(At, 0, 0); PG8_STAGE(PG8_SA(1, 1), a1 + hstep, voffA);
;             PG8_WAIT_V(8); PG8_WAIT_L(0); PG8_BAR; PG8_MMA(0, 0, At, B0); PG8_MMA(0, 1, At, B1); PG8_BAR; PG8_SCHED;
;             PG8_LDA(At, 0, 1); PG8_STAGE(PG8_SB(0, 0), b2, voffB); PG8_STAGE(PG8_SB(0, 1), b2 + hstep, voffB); PG8_STAGE(PG8_SA(0, 0), a2, voffA);
.LBB0_350:
	s_add_u32 s24, s22, 0xfffc0080
	s_addc_u32 s25, s23, -1
	s_add_i32 s48, 0, 0x10000
	s_cmp_eq_u32 s47, 12
	s_cselect_b32 s27, s13, s25
	s_cselect_b32 s26, s19, s24
	s_cselect_b32 s25, s11, s46
	s_cselect_b32 s24, s33, s45
	s_add_i32 s50, 0, 0x14000
	v_add_u32_e32 v126, s48, v183
	v_add_u32_e32 v168, s50, v183
	ds_read_b128 v[114:117], v126
	ds_read_b128 v[118:121], v126 offset:1024
	ds_read_b128 v[122:125], v126 offset:2048
	ds_read_b128 v[126:129], v126 offset:3072
	ds_read_b128 v[130:133], v168
	ds_read_b128 v[134:137], v168 offset:1024
	ds_read_b128 v[164:167], v168 offset:2048
	ds_read_b128 v[168:171], v168 offset:3072
	v_lshl_add_u64 v[180:181], s[22:23], 0, v[160:161]
	s_add_i32 m0, s21, 0xc000
	ds_read_b128 v[172:175], v185
	ds_read_b128 v[176:179], v185 offset:1024
	ds_read_b128 v[186:189], v185 offset:2048
	ds_read_b128 v[190:193], v185 offset:3072
	ds_read_b128 v[194:197], v185 offset:4096
	ds_read_b128 v[198:201], v185 offset:5120
	ds_read_b128 v[202:205], v185 offset:6144
	ds_read_b128 v[206:209], v185 offset:7168
	global_load_lds_dwordx4 v[180:181], off
	v_lshl_add_u64 v[180:181], s[22:23], 0, v[162:163]
	s_add_i32 m0, s21, 0xe000
	s_nop 0
	global_load_lds_dwordx4 v[180:181], off
	s_waitcnt vmcnt(8)
	s_waitcnt lgkmcnt(0)
	s_setprio 1
	s_barrier
	s_waitcnt lgkmcnt(0)
	v_mfma_f32_16x16x32_bf16 v[150:153], v[114:117], v[172:175], v[150:153]
	v_mfma_f32_16x16x32_bf16 v[146:149], v[122:125], v[172:175], v[146:149]
	v_mfma_f32_16x16x32_bf16 v[110:113], v[114:117], v[186:189], v[110:113]
	v_mfma_f32_16x16x32_bf16 v[106:109], v[122:125], v[186:189], v[106:109]
	v_mfma_f32_16x16x32_bf16 v[94:97], v[114:117], v[194:197], v[94:97]
	v_mfma_f32_16x16x32_bf16 v[90:93], v[122:125], v[194:197], v[90:93]
	v_mfma_f32_16x16x32_bf16 v[78:81], v[114:117], v[202:205], v[78:81]
	v_mfma_f32_16x16x32_bf16 v[74:77], v[122:125], v[202:205], v[74:77]
	v_mfma_f32_16x16x32_bf16 v[150:153], v[118:121], v[176:179], v[150:153]
	v_mfma_f32_16x16x32_bf16 v[146:149], v[126:129], v[176:179], v[146:149]
	v_mfma_f32_16x16x32_bf16 v[110:113], v[118:121], v[190:193], v[110:113]
	v_mfma_f32_16x16x32_bf16 v[106:109], v[126:129], v[190:193], v[106:109]
	v_mfma_f32_16x16x32_bf16 v[94:97], v[118:121], v[198:201], v[94:97]
	v_mfma_f32_16x16x32_bf16 v[90:93], v[126:129], v[198:201], v[90:93]
	v_mfma_f32_16x16x32_bf16 v[78:81], v[118:121], v[206:209], v[78:81]
	v_mfma_f32_16x16x32_bf16 v[74:77], v[126:129], v[206:209], v[74:77]
	s_setprio 0
	s_setprio 1
	v_mfma_f32_16x16x32_bf16 v[142:145], v[130:133], v[172:175], v[142:145]
	v_mfma_f32_16x16x32_bf16 v[138:141], v[164:167], v[172:175], v[138:141]
	v_mfma_f32_16x16x32_bf16 v[102:105], v[130:133], v[186:189], v[102:105]
	v_mfma_f32_16x16x32_bf16 v[98:101], v[164:167], v[186:189], v[98:101]
	v_mfma_f32_16x16x32_bf16 v[86:89], v[130:133], v[194:197], v[86:89]
	v_mfma_f32_16x16x32_bf16 v[82:85], v[164:167], v[194:197], v[82:85]
	v_mfma_f32_16x16x32_bf16 v[70:73], v[130:133], v[202:205], v[70:73]
	v_mfma_f32_16x16x32_bf16 v[66:69], v[164:167], v[202:205], v[66:69]
	v_mfma_f32_16x16x32_bf16 v[142:145], v[134:137], v[176:179], v[142:145]
	v_mfma_f32_16x16x32_bf16 v[138:141], v[168:171], v[176:179], v[138:141]
	v_mfma_f32_16x16x32_bf16 v[102:105], v[134:137], v[190:193], v[102:105]
	v_mfma_f32_16x16x32_bf16 v[98:101], v[168:171], v[190:193], v[98:101]
	v_mfma_f32_16x16x32_bf16 v[86:89], v[134:137], v[198:201], v[86:89]
	v_mfma_f32_16x16x32_bf16 v[82:85], v[168:171], v[198:201], v[82:85]
	v_mfma_f32_16x16x32_bf16 v[70:73], v[134:137], v[206:209], v[70:73]
	v_mfma_f32_16x16x32_bf16 v[66:69], v[168:171], v[206:209], v[66:69]
	s_barrier
	s_add_i32 s48, s48, s36
	v_lshl_add_u64 v[180:181], s[24:25], 0, v[0:1]
	s_mov_b32 m0, s48
	ds_read_b128 v[172:175], v185 offset:16384
	ds_read_b128 v[176:179], v185 offset:17408
	ds_read_b128 v[186:189], v185 offset:18432
	ds_read_b128 v[190:193], v185 offset:19456
	ds_read_b128 v[194:197], v185 offset:20480
	ds_read_b128 v[198:201], v185 offset:21504
	ds_read_b128 v[202:205], v185 offset:22528
	ds_read_b128 v[206:209], v185 offset:23552
	s_setprio 0
	global_load_lds_dwordx4 v[180:181], off
	s_add_i32 m0, s48, 0x2000
	s_add_u32 s48, s24, 0x40000
	v_lshl_add_u64 v[210:211], s[24:25], 0, v[158:159]
	s_addc_u32 s49, s25, 0
	s_add_i32 s50, s50, s36
	global_load_lds_dwordx4 v[210:211], off
	v_lshl_add_u64 v[212:213], s[48:49], 0, v[0:1]
	s_mov_b32 m0, s50
	v_lshl_add_u64 v[214:215], s[26:27], 0, v[156:157]
	global_load_lds_dwordx4 v[212:213], off
	v_lshl_add_u64 v[212:213], s[48:49], 0, v[158:159]
	s_add_i32 m0, s50, 0x2000
	s_nop 0
	global_load_lds_dwordx4 v[212:213], off
	v_lshl_add_u64 v[212:213], s[26:27], 0, v[154:155]
	s_mov_b32 m0, s21
	s_nop 0
	global_load_lds_dwordx4 v[212:213], off
	s_mov_b32 m0, s37
	s_nop 0
	global_load_lds_dwordx4 v[214:215], off
	s_waitcnt vmcnt(8)
	s_waitcnt lgkmcnt(0)
	s_setprio 1
	s_barrier
; #define PG8_STAGE(bufoff, gbase, voff) do { _Pragma("unroll") for (int _i = 0; _i < 2; ++_i) \
;         __builtin_amdgcn_global_load_lds((const unsigned*)((const char*)(gbase) + (voff)[_i]), (PG8_LAS unsigned*)(lds + (bufoff) + ldsw + _i * 8192), 16, 0, 0); } while (0)
; #define PG8_LDA(dst, b, h) do { _Pragma("unroll") for (int m = 0; m < 4; ++m) _Pragma("unroll") for (int k = 0; k < 2; ++k) dst[m][k] = *(const PG8_LAS bf16x8*)(lds + PG8_SA(b, h) + aoff + m * 2048 + k * 1024); } while (0)
; #define PG8_LDB(dst, b, h) do { _Pragma("unroll") for (int n = 0; n < 2; ++n) _Pragma("unroll") for (int k = 0; k < 2; ++k) dst[n][k] = *(const PG8_LAS bf16x8*)(lds + PG8_SB(b, h) + boff + n * 2048 + k * 1024); } while (0)
; #define PG8_MMA(ai, bj, At, Bt) do { __builtin_amdgcn_s_setprio(1); _Pragma("unroll") for (int m = 0; m < 4; ++m) _Pragma("unroll") for (int n = 0; n < 2; ++n) _Pragma("unroll") for (int k = 0; k < 2; ++k) \
;         acc[ai][bj][m][n] = __builtin_amdgcn_mfma_f32_16x16x32_bf16(Bt[n][k], At[m][k], acc[ai][bj][m][n], 0, 0, 0); __builtin_amdgcn_s_setprio(0); } while (0)
; #define PG8_WAIT_V(n) asm volatile("s_waitcnt vmcnt(" #n ")" ::: "memory")
; #define PG8_WAIT_L(n) asm volatile("s_waitcnt lgkmcnt(" #n ")" ::: "memory")
; #define PG8_BAR __builtin_amdgcn_s_barrier()
; #define PG8_SCHED __builtin_amdgcn_sched_barrier(0)
; template <class Epi, class Sched, bool ALIGN_EPI = false, bool SP2 = false>
; __device__ __forceinline__ void gemm_phase(PG8_LAS unsigned char* lds, const Gemm g, const Sched& S, const Epi& E, const int wv) {
;     ...
;             PG8_WAIT_V(8); PG8_WAIT_L(0); PG8_BAR; PG8_MMA(1, 0, At, B0); PG8_MMA(1, 1, At, B1); PG8_BAR; PG8_SCHED;
;             PG8_LDB(B0, 1, 0); PG8_LDB(B1, 1, 1); PG8_SCHED; PG8_LDA(At, 1, 0); PG8_STAGE(PG8_SA(0, 1), a2 + hstep, voffA);
;             PG8_WAIT_V(8); PG8_WAIT_L(0); PG8_BAR; PG8_MMA(0, 0, At, B0); PG8_MMA(0, 1, At, B1); PG8_BAR; PG8_SCHED;
	s_waitcnt lgkmcnt(0)
	v_mfma_f32_16x16x32_bf16 v[62:65], v[114:117], v[172:175], v[62:65]
	v_mfma_f32_16x16x32_bf16 v[58:61], v[122:125], v[172:175], v[58:61]
	v_mfma_f32_16x16x32_bf16 v[46:49], v[114:117], v[186:189], v[46:49]
	v_mfma_f32_16x16x32_bf16 v[42:45], v[122:125], v[186:189], v[42:45]
	v_mfma_f32_16x16x32_bf16 v[30:33], v[114:117], v[194:197], v[30:33]
	v_mfma_f32_16x16x32_bf16 v[26:29], v[122:125], v[194:197], v[26:29]
	v_mfma_f32_16x16x32_bf16 v[14:17], v[114:117], v[202:205], v[14:17]
	v_mfma_f32_16x16x32_bf16 v[10:13], v[122:125], v[202:205], v[10:13]
	v_mfma_f32_16x16x32_bf16 v[62:65], v[118:121], v[176:179], v[62:65]
	v_mfma_f32_16x16x32_bf16 v[58:61], v[126:129], v[176:179], v[58:61]
	v_mfma_f32_16x16x32_bf16 v[46:49], v[118:121], v[190:193], v[46:49]
	v_mfma_f32_16x16x32_bf16 v[42:45], v[126:129], v[190:193], v[42:45]
	v_mfma_f32_16x16x32_bf16 v[30:33], v[118:121], v[198:201], v[30:33]
	v_mfma_f32_16x16x32_bf16 v[26:29], v[126:129], v[198:201], v[26:29]
	v_mfma_f32_16x16x32_bf16 v[14:17], v[118:121], v[206:209], v[14:17]
	v_mfma_f32_16x16x32_bf16 v[10:13], v[126:129], v[206:209], v[10:13]
	s_setprio 0
	s_setprio 1
	v_mfma_f32_16x16x32_bf16 v[54:57], v[130:133], v[172:175], v[54:57]
	v_mfma_f32_16x16x32_bf16 v[50:53], v[164:167], v[172:175], v[50:53]
	v_mfma_f32_16x16x32_bf16 v[38:41], v[130:133], v[186:189], v[38:41]
	v_mfma_f32_16x16x32_bf16 v[34:37], v[164:167], v[186:189], v[34:37]
	v_mfma_f32_16x16x32_bf16 v[22:25], v[130:133], v[194:197], v[22:25]
	v_mfma_f32_16x16x32_bf16 v[18:21], v[164:167], v[194:197], v[18:21]
	v_mfma_f32_16x16x32_bf16 v[6:9], v[130:133], v[202:205], v[6:9]
	v_mfma_f32_16x16x32_bf16 v[2:5], v[164:167], v[202:205], v[2:5]
	v_mfma_f32_16x16x32_bf16 v[54:57], v[134:137], v[176:179], v[54:57]
	v_mfma_f32_16x16x32_bf16 v[50:53], v[168:171], v[176:179], v[50:53]
	v_mfma_f32_16x16x32_bf16 v[38:41], v[134:137], v[190:193], v[38:41]
	v_mfma_f32_16x16x32_bf16 v[34:37], v[168:171], v[190:193], v[34:37]
	v_mfma_f32_16x16x32_bf16 v[22:25], v[134:137], v[198:201], v[22:25]
	v_mfma_f32_16x16x32_bf16 v[18:21], v[168:171], v[198:201], v[18:21]
	v_mfma_f32_16x16x32_bf16 v[6:9], v[134:137], v[206:209], v[6:9]
	v_mfma_f32_16x16x32_bf16 v[2:5], v[168:171], v[206:209], v[2:5]
	s_barrier
	s_add_i32 s48, 0, 0x18000
	s_add_i32 s49, 0, 0x1c000
	v_add_u32_e32 v126, s48, v183
	v_add_u32_e32 v168, s49, v183
	ds_read_b128 v[114:117], v126
	ds_read_b128 v[118:121], v126 offset:1024
	ds_read_b128 v[122:125], v126 offset:2048
	ds_read_b128 v[126:129], v126 offset:3072
	ds_read_b128 v[130:133], v168
	ds_read_b128 v[134:137], v168 offset:1024
	ds_read_b128 v[164:167], v168 offset:2048
	ds_read_b128 v[168:171], v168 offset:3072
	s_setprio 0
	s_add_u32 s26, s26, 0x40000
	s_addc_u32 s27, s27, 0
	s_mov_b32 m0, s38
	v_lshl_add_u64 v[216:217], s[26:27], 0, v[154:155]
	ds_read_b128 v[172:175], v185 offset:32768
	ds_read_b128 v[176:179], v185 offset:33792
	ds_read_b128 v[186:189], v185 offset:34816
	ds_read_b128 v[190:193], v185 offset:35840
	ds_read_b128 v[194:197], v185 offset:36864
	ds_read_b128 v[198:201], v185 offset:37888
	ds_read_b128 v[202:205], v185 offset:38912
	ds_read_b128 v[206:209], v185 offset:39936
	global_load_lds_dwordx4 v[216:217], off
	v_lshl_add_u64 v[216:217], s[26:27], 0, v[156:157]
	s_mov_b32 m0, s39
	s_nop 0
	global_load_lds_dwordx4 v[216:217], off
	s_waitcnt vmcnt(8)
	s_waitcnt lgkmcnt(0)
	s_setprio 1
	s_barrier
	s_waitcnt lgkmcnt(0)
	v_mfma_f32_16x16x32_bf16 v[150:153], v[114:117], v[172:175], v[150:153]
	v_mfma_f32_16x16x32_bf16 v[146:149], v[122:125], v[172:175], v[146:149]
	v_mfma_f32_16x16x32_bf16 v[110:113], v[114:117], v[186:189], v[110:113]
	v_mfma_f32_16x16x32_bf16 v[106:109], v[122:125], v[186:189], v[106:109]
	v_mfma_f32_16x16x32_bf16 v[94:97], v[114:117], v[194:197], v[94:97]
	v_mfma_f32_16x16x32_bf16 v[90:93], v[122:125], v[194:197], v[90:93]
	v_mfma_f32_16x16x32_bf16 v[78:81], v[114:117], v[202:205], v[78:81]
	v_mfma_f32_16x16x32_bf16 v[74:77], v[122:125], v[202:205], v[74:77]
	v_mfma_f32_16x16x32_bf16 v[150:153], v[118:121], v[176:179], v[150:153]
	v_mfma_f32_16x16x32_bf16 v[146:149], v[126:129], v[176:179], v[146:149]
	v_mfma_f32_16x16x32_bf16 v[110:113], v[118:121], v[190:193], v[110:113]
	v_mfma_f32_16x16x32_bf16 v[106:109], v[126:129], v[190:193], v[106:109]
	v_mfma_f32_16x16x32_bf16 v[94:97], v[118:121], v[198:201], v[94:97]
	v_mfma_f32_16x16x32_bf16 v[90:93], v[126:129], v[198:201], v[90:93]
	v_mfma_f32_16x16x32_bf16 v[78:81], v[118:121], v[206:209], v[78:81]
	v_mfma_f32_16x16x32_bf16 v[74:77], v[126:129], v[206:209], v[74:77]
	s_setprio 0
	s_setprio 1
	v_mfma_f32_16x16x32_bf16 v[142:145], v[130:133], v[172:175], v[142:145]
	v_mfma_f32_16x16x32_bf16 v[138:141], v[164:167], v[172:175], v[138:141]
	v_mfma_f32_16x16x32_bf16 v[102:105], v[130:133], v[186:189], v[102:105]
	v_mfma_f32_16x16x32_bf16 v[98:101], v[164:167], v[186:189], v[98:101]
	v_mfma_f32_16x16x32_bf16 v[86:89], v[130:133], v[194:197], v[86:89]
	v_mfma_f32_16x16x32_bf16 v[82:85], v[164:167], v[194:197], v[82:85]
	v_mfma_f32_16x16x32_bf16 v[70:73], v[130:133], v[202:205], v[70:73]
	v_mfma_f32_16x16x32_bf16 v[66:69], v[164:167], v[202:205], v[66:69]
	v_mfma_f32_16x16x32_bf16 v[142:145], v[134:137], v[176:179], v[142:145]
	v_mfma_f32_16x16x32_bf16 v[138:141], v[168:171], v[176:179], v[138:141]
	v_mfma_f32_16x16x32_bf16 v[102:105], v[134:137], v[190:193], v[102:105]
	v_mfma_f32_16x16x32_bf16 v[98:101], v[168:171], v[190:193], v[98:101]
	v_mfma_f32_16x16x32_bf16 v[86:89], v[134:137], v[198:201], v[86:89]
	v_mfma_f32_16x16x32_bf16 v[82:85], v[168:171], v[198:201], v[82:85]
	v_mfma_f32_16x16x32_bf16 v[70:73], v[134:137], v[206:209], v[70:73]
	v_mfma_f32_16x16x32_bf16 v[66:69], v[168:171], v[206:209], v[66:69]
	s_barrier
; #define PG8_STAGE(bufoff, gbase, voff) do { _Pragma("unroll") for (int _i = 0; _i < 2; ++_i) \
;         __builtin_amdgcn_global_load_lds((const unsigned*)((const char*)(gbase) + (voff)[_i]), (PG8_LAS unsigned*)(lds + (bufoff) + ldsw + _i * 8192), 16, 0, 0); } while (0)
; #define PG8_LDA(dst, b, h) do { _Pragma("unroll") for (int m = 0; m < 4; ++m) _Pragma("unroll") for (int k = 0; k < 2; ++k) dst[m][k] = *(const PG8_LAS bf16x8*)(lds + PG8_SA(b, h) + aoff + m * 2048 + k * 1024); } while (0)
; #define PG8_MMA(ai, bj, At, Bt) do { __builtin_amdgcn_s_setprio(1); _Pragma("unroll") for (int m = 0; m < 4; ++m) _Pragma("unroll") for (int n = 0; n < 2; ++n) _Pragma("unroll") for (int k = 0; k < 2; ++k) \
;         acc[ai][bj][m][n] = __builtin_amdgcn_mfma_f32_16x16x32_bf16(Bt[n][k], At[m][k], acc[ai][bj][m][n], 0, 0, 0); __builtin_amdgcn_s_setprio(0); } while (0)
; #define PG8_WAIT_V(n) asm volatile("s_waitcnt vmcnt(" #n ")" ::: "memory")
; #define PG8_WAIT_L(n) asm volatile("s_waitcnt lgkmcnt(" #n ")" ::: "memory")
; #define PG8_BAR __builtin_amdgcn_s_barrier()
; #define PG8_SCHED __builtin_amdgcn_sched_barrier(0)
; template <class Epi, class Sched, bool ALIGN_EPI = false, bool SP2 = false>
; __device__ __forceinline__ void gemm_phase(PG8_LAS unsigned char* lds, const Gemm g, const Sched& S, const Epi& E, const int wv) {
;     ...
;             PG8_LDA(At, 1, 1); PG8_STAGE(PG8_SB(1, 0), b3, voffB); PG8_STAGE(PG8_SB(1, 1), b3 + hstep, voffB); PG8_STAGE(PG8_SA(1, 0), a3, voffA);
;             PG8_WAIT_V(8); PG8_WAIT_L(0); PG8_BAR; PG8_MMA(1, 0, At, B0); PG8_MMA(1, 1, At, B1); PG8_BAR; PG8_SCHED;
	s_add_i32 s26, s48, s36
	v_lshl_add_u64 v[180:181], v[180:181], 0, s[2:3]
	s_mov_b32 m0, s26
	ds_read_b128 v[172:175], v185 offset:49152
	ds_read_b128 v[176:179], v185 offset:50176
	ds_read_b128 v[186:189], v185 offset:51200
	ds_read_b128 v[190:193], v185 offset:52224
	ds_read_b128 v[194:197], v185 offset:53248
	ds_read_b128 v[198:201], v185 offset:54272
	ds_read_b128 v[202:205], v185 offset:55296
	ds_read_b128 v[206:209], v185 offset:56320
	s_setprio 0
	global_load_lds_dwordx4 v[180:181], off
	s_add_i32 m0, s26, 0x2000
	s_add_u32 s24, s24, 0x40080
	v_lshl_add_u64 v[180:181], v[210:211], 0, s[2:3]
	s_addc_u32 s25, s25, 0
	s_add_i32 s26, s49, s36
	global_load_lds_dwordx4 v[180:181], off
	v_lshl_add_u64 v[180:181], s[24:25], 0, v[0:1]
	s_mov_b32 m0, s26
	s_nop 0
	global_load_lds_dwordx4 v[180:181], off
	v_lshl_add_u64 v[180:181], s[24:25], 0, v[158:159]
	s_add_i32 m0, s26, 0x2000
	s_nop 0
	global_load_lds_dwordx4 v[180:181], off
	v_lshl_add_u64 v[180:181], v[212:213], 0, s[2:3]
	s_mov_b32 m0, s40
	s_nop 0
	global_load_lds_dwordx4 v[180:181], off
	v_lshl_add_u64 v[180:181], v[214:215], 0, s[2:3]
	s_mov_b32 m0, s41
	s_nop 0
	global_load_lds_dwordx4 v[180:181], off
	s_waitcnt vmcnt(8)
	s_waitcnt lgkmcnt(0)
	s_setprio 1
	s_barrier
	s_waitcnt lgkmcnt(0)
	v_mfma_f32_16x16x32_bf16 v[62:65], v[114:117], v[172:175], v[62:65]
	v_mfma_f32_16x16x32_bf16 v[58:61], v[122:125], v[172:175], v[58:61]
	v_mfma_f32_16x16x32_bf16 v[46:49], v[114:117], v[186:189], v[46:49]
	v_mfma_f32_16x16x32_bf16 v[42:45], v[122:125], v[186:189], v[42:45]
	v_mfma_f32_16x16x32_bf16 v[30:33], v[114:117], v[194:197], v[30:33]
	v_mfma_f32_16x16x32_bf16 v[26:29], v[122:125], v[194:197], v[26:29]
	v_mfma_f32_16x16x32_bf16 v[14:17], v[114:117], v[202:205], v[14:17]
	v_mfma_f32_16x16x32_bf16 v[10:13], v[122:125], v[202:205], v[10:13]
	v_mfma_f32_16x16x32_bf16 v[62:65], v[118:121], v[176:179], v[62:65]
	v_mfma_f32_16x16x32_bf16 v[58:61], v[126:129], v[176:179], v[58:61]
	v_mfma_f32_16x16x32_bf16 v[46:49], v[118:121], v[190:193], v[46:49]
	v_mfma_f32_16x16x32_bf16 v[42:45], v[126:129], v[190:193], v[42:45]
	v_mfma_f32_16x16x32_bf16 v[30:33], v[118:121], v[198:201], v[30:33]
	v_mfma_f32_16x16x32_bf16 v[26:29], v[126:129], v[198:201], v[26:29]
	v_mfma_f32_16x16x32_bf16 v[14:17], v[118:121], v[206:209], v[14:17]
	v_mfma_f32_16x16x32_bf16 v[10:13], v[126:129], v[206:209], v[10:13]
	s_setprio 0
	s_setprio 1
	v_mfma_f32_16x16x32_bf16 v[54:57], v[130:133], v[172:175], v[54:57]
	v_mfma_f32_16x16x32_bf16 v[50:53], v[164:167], v[172:175], v[50:53]
	v_mfma_f32_16x16x32_bf16 v[38:41], v[130:133], v[186:189], v[38:41]
	v_mfma_f32_16x16x32_bf16 v[34:37], v[164:167], v[186:189], v[34:37]
	v_mfma_f32_16x16x32_bf16 v[22:25], v[130:133], v[194:197], v[22:25]
	v_mfma_f32_16x16x32_bf16 v[18:21], v[164:167], v[194:197], v[18:21]
	v_mfma_f32_16x16x32_bf16 v[6:9], v[130:133], v[202:205], v[6:9]
	v_mfma_f32_16x16x32_bf16 v[2:5], v[164:167], v[202:205], v[2:5]
	v_mfma_f32_16x16x32_bf16 v[54:57], v[134:137], v[176:179], v[54:57]
	v_mfma_f32_16x16x32_bf16 v[50:53], v[168:171], v[176:179], v[50:53]
	v_mfma_f32_16x16x32_bf16 v[38:41], v[134:137], v[190:193], v[38:41]
	v_mfma_f32_16x16x32_bf16 v[34:37], v[168:171], v[190:193], v[34:37]
	v_mfma_f32_16x16x32_bf16 v[22:25], v[134:137], v[198:201], v[22:25]
	v_mfma_f32_16x16x32_bf16 v[18:21], v[168:171], v[198:201], v[18:21]
	v_mfma_f32_16x16x32_bf16 v[6:9], v[134:137], v[206:209], v[6:9]
	v_mfma_f32_16x16x32_bf16 v[2:5], v[168:171], v[206:209], v[2:5]
	s_barrier
	s_setprio 0
	s_add_i32 s47, s47, 2
	s_add_u32 s22, s22, 0x100
	s_addc_u32 s23, s23, 0
	s_add_u32 s45, s45, 0x100
	s_addc_u32 s46, s46, 0
	s_cmp_gt_u32 s47, 13
	s_cbranch_scc0 .LBB0_350
	s_and_b64 vcc, exec, s[8:9]
	s_cbranch_vccz .LBB0_353
	s_barrier

; #define PG8_STAGE(bufoff, gbase, voff) do { _Pragma("unroll") for (int _i = 0; _i < 2; ++_i) \
;         __builtin_amdgcn_global_load_lds((const unsigned*)((const char*)(gbase) + (voff)[_i]), (PG8_LAS unsigned*)(lds + (bufoff) + ldsw + _i * 8192), 16, 0, 0); } while (0)
; #define PG8_LDA(dst, b, h) do { _Pragma("unroll") for (int m = 0; m < 4; ++m) _Pragma("unroll") for (int k = 0; k < 2; ++k) dst[m][k] = *(const PG8_LAS bf16x8*)(lds + PG8_SA(b, h) + aoff + m * 2048 + k * 1024); } while (0)
; #define PG8_LDB(dst, b, h) do { _Pragma("unroll") for (int n = 0; n < 2; ++n) _Pragma("unroll") for (int k = 0; k < 2; ++k) dst[n][k] = *(const PG8_LAS bf16x8*)(lds + PG8_SB(b, h) + boff + n * 2048 + k * 1024); } while (0)
; #define PG8_MMA(ai, bj, At, Bt) do { __builtin_amdgcn_s_setprio(1); _Pragma("unroll") for (int m = 0; m < 4; ++m) _Pragma("unroll") for (int n = 0; n < 2; ++n) _Pragma("unroll") for (int k = 0; k < 2; ++k) \
;         acc[ai][bj][m][n] = __builtin_amdgcn_mfma_f32_16x16x32_bf16(Bt[n][k], At[m][k], acc[ai][bj][m][n], 0, 0, 0); __builtin_amdgcn_s_setprio(0); } while (0)
; #define PG8_WAIT_V(n) asm volatile("s_waitcnt vmcnt(" #n ")" ::: "memory")
; #define PG8_WAIT_L(n) asm volatile("s_waitcnt lgkmcnt(" #n ")" ::: "memory")
; #define PG8_BAR __builtin_amdgcn_s_barrier()
; #define PG8_SCHED __builtin_amdgcn_sched_barrier(0)
; template <class Epi, class Sched, bool ALIGN_EPI = false, bool SP2 = false>
; __device__ __forceinline__ void gemm_phase(PG8_LAS unsigned char* lds, const Gemm g, const Sched& S, const Epi& E, const int wv) {
;     ...
;             const bool last = (t == nt - 2);
;             const char* a1 = cA + (size_t)(t + 1) * kstep;
;             const char* a2 = last ? nA : cA + (size_t)(t + 2) * kstep; const char* b2 = last ? nB : cB + (size_t)(t + 2) * kstep;
;             const char* a3 = a2 + kstep; const char* b3 = b2 + kstep;
;             if (last && has_next) S.a_ready(nxt);
;             if constexpr (SP2) {
;             PG8_LDB(B0, 0, 0); PG8_LDB(B1, 0, 1); PG8_SCHED; PG8_LDA(At, 0, 0); PG8_STAGE(PG8_SA(1, 1), a1 + hstep, voffA);
;             PG8_WAIT_V(8); PG8_WAIT_L(0); PG8_BAR; PG8_MMA(0, 0, At, B0); PG8_MMA(0, 1, At, B1); PG8_BAR; PG8_SCHED;
;             PG8_LDA(At, 0, 1); PG8_STAGE(PG8_SB(0, 0), b2, voffB); PG8_STAGE(PG8_SB(0, 1), b2 + hstep, voffB); PG8_STAGE(PG8_SA(0, 0), a2, voffA);
.LBB0_428:
	s_add_u32 s20, s18, 0xfffc0080
	s_addc_u32 s21, s19, -1
	s_add_i32 s46, 0, 0x10000
	s_cmp_eq_u32 s45, 12
	s_cselect_b32 s23, s11, s21
	s_cselect_b32 s22, s33, s20
	s_cselect_b32 s21, s9, s44
	s_cselect_b32 s20, s42, s43
	s_add_i32 s48, 0, 0x14000
	v_add_u32_e32 v152, s46, v166
	v_add_u32_e32 v164, s48, v166
	ds_read_b128 v[140:143], v152
	ds_read_b128 v[144:147], v152 offset:1024
	ds_read_b128 v[148:151], v152 offset:2048
	ds_read_b128 v[152:155], v152 offset:3072
	ds_read_b128 v[156:159], v164
	ds_read_b128 v[160:163], v164 offset:1024
	ds_read_b128 v[170:173], v164 offset:2048
	ds_read_b128 v[174:177], v164 offset:3072
	v_lshl_add_u64 v[210:211], s[18:19], 0, v[136:137]
	s_add_i32 m0, s30, 0xc000
	ds_read_b128 v[178:181], v168
	ds_read_b128 v[182:185], v168 offset:1024
	ds_read_b128 v[186:189], v168 offset:2048
	ds_read_b128 v[190:193], v168 offset:3072
	ds_read_b128 v[194:197], v168 offset:4096
	ds_read_b128 v[198:201], v168 offset:5120
	ds_read_b128 v[202:205], v168 offset:6144
	ds_read_b128 v[206:209], v168 offset:7168
	global_load_lds_dwordx4 v[210:211], off
	v_lshl_add_u64 v[210:211], s[18:19], 0, v[138:139]
	s_add_i32 m0, s30, 0xe000
	s_nop 0
	global_load_lds_dwordx4 v[210:211], off
	s_waitcnt vmcnt(8)
	s_waitcnt lgkmcnt(0)
	s_setprio 1
	s_barrier
	s_waitcnt lgkmcnt(0)
	v_mfma_f32_16x16x32_bf16 v[126:129], v[140:143], v[178:181], v[126:129]
	v_mfma_f32_16x16x32_bf16 v[118:121], v[148:151], v[178:181], v[118:121]
	v_mfma_f32_16x16x32_bf16 v[110:113], v[140:143], v[186:189], v[110:113]
	v_mfma_f32_16x16x32_bf16 v[102:105], v[148:151], v[186:189], v[102:105]
	v_mfma_f32_16x16x32_bf16 v[94:97], v[140:143], v[194:197], v[94:97]
	v_mfma_f32_16x16x32_bf16 v[86:89], v[148:151], v[194:197], v[86:89]
	v_mfma_f32_16x16x32_bf16 v[78:81], v[140:143], v[202:205], v[78:81]
	v_mfma_f32_16x16x32_bf16 v[70:73], v[148:151], v[202:205], v[70:73]
	v_mfma_f32_16x16x32_bf16 v[126:129], v[144:147], v[182:185], v[126:129]
	v_mfma_f32_16x16x32_bf16 v[118:121], v[152:155], v[182:185], v[118:121]
	v_mfma_f32_16x16x32_bf16 v[110:113], v[144:147], v[190:193], v[110:113]
	v_mfma_f32_16x16x32_bf16 v[102:105], v[152:155], v[190:193], v[102:105]
	v_mfma_f32_16x16x32_bf16 v[94:97], v[144:147], v[198:201], v[94:97]
	v_mfma_f32_16x16x32_bf16 v[86:89], v[152:155], v[198:201], v[86:89]
	v_mfma_f32_16x16x32_bf16 v[78:81], v[144:147], v[206:209], v[78:81]
	v_mfma_f32_16x16x32_bf16 v[70:73], v[152:155], v[206:209], v[70:73]
	s_setprio 0
	s_setprio 1
	v_mfma_f32_16x16x32_bf16 v[122:125], v[156:159], v[178:181], v[122:125]
	v_mfma_f32_16x16x32_bf16 v[114:117], v[170:173], v[178:181], v[114:117]
	v_mfma_f32_16x16x32_bf16 v[106:109], v[156:159], v[186:189], v[106:109]
	v_mfma_f32_16x16x32_bf16 v[98:101], v[170:173], v[186:189], v[98:101]
	v_mfma_f32_16x16x32_bf16 v[90:93], v[156:159], v[194:197], v[90:93]
	v_mfma_f32_16x16x32_bf16 v[82:85], v[170:173], v[194:197], v[82:85]
	v_mfma_f32_16x16x32_bf16 v[74:77], v[156:159], v[202:205], v[74:77]
	v_mfma_f32_16x16x32_bf16 v[66:69], v[170:173], v[202:205], v[66:69]
	v_mfma_f32_16x16x32_bf16 v[122:125], v[160:163], v[182:185], v[122:125]
	v_mfma_f32_16x16x32_bf16 v[114:117], v[174:177], v[182:185], v[114:117]
	v_mfma_f32_16x16x32_bf16 v[106:109], v[160:163], v[190:193], v[106:109]
	v_mfma_f32_16x16x32_bf16 v[98:101], v[174:177], v[190:193], v[98:101]
	v_mfma_f32_16x16x32_bf16 v[90:93], v[160:163], v[198:201], v[90:93]
	v_mfma_f32_16x16x32_bf16 v[82:85], v[174:177], v[198:201], v[82:85]
	v_mfma_f32_16x16x32_bf16 v[74:77], v[160:163], v[206:209], v[74:77]
	v_mfma_f32_16x16x32_bf16 v[66:69], v[174:177], v[206:209], v[66:69]
	s_barrier
	s_add_i32 s46, s46, s29
	v_lshl_add_u64 v[210:211], s[20:21], 0, v[0:1]
	s_mov_b32 m0, s46
	ds_read_b128 v[178:181], v168 offset:16384
	ds_read_b128 v[182:185], v168 offset:17408
	ds_read_b128 v[186:189], v168 offset:18432
	ds_read_b128 v[190:193], v168 offset:19456
	ds_read_b128 v[194:197], v168 offset:20480
	ds_read_b128 v[198:201], v168 offset:21504
	ds_read_b128 v[202:205], v168 offset:22528
	ds_read_b128 v[206:209], v168 offset:23552
	s_setprio 0
	global_load_lds_dwordx4 v[210:211], off
	s_add_i32 m0, s46, 0x2000
	s_add_u32 s46, s20, 0x40000
	v_lshl_add_u64 v[212:213], s[20:21], 0, v[130:131]
	s_addc_u32 s47, s21, 0
	s_add_i32 s48, s48, s29
	global_load_lds_dwordx4 v[212:213], off
	v_lshl_add_u64 v[214:215], s[46:47], 0, v[0:1]
	s_mov_b32 m0, s48
	v_lshl_add_u64 v[216:217], s[22:23], 0, v[132:133]
	global_load_lds_dwordx4 v[214:215], off
	v_lshl_add_u64 v[214:215], s[46:47], 0, v[130:131]
	s_add_i32 m0, s48, 0x2000
	s_nop 0
	global_load_lds_dwordx4 v[214:215], off
	v_lshl_add_u64 v[214:215], s[22:23], 0, v[134:135]
	s_mov_b32 m0, s30
	s_nop 0
	global_load_lds_dwordx4 v[214:215], off
	s_mov_b32 m0, s31
	s_nop 0
	global_load_lds_dwordx4 v[216:217], off
	s_waitcnt vmcnt(8)
	s_waitcnt lgkmcnt(0)
	s_setprio 1
	s_barrier
; #define PG8_STAGE(bufoff, gbase, voff) do { _Pragma("unroll") for (int _i = 0; _i < 2; ++_i) \
;         __builtin_amdgcn_global_load_lds((const unsigned*)((const char*)(gbase) + (voff)[_i]), (PG8_LAS unsigned*)(lds + (bufoff) + ldsw + _i * 8192), 16, 0, 0); } while (0)
; #define PG8_LDA(dst, b, h) do { _Pragma("unroll") for (int m = 0; m < 4; ++m) _Pragma("unroll") for (int k = 0; k < 2; ++k) dst[m][k] = *(const PG8_LAS bf16x8*)(lds + PG8_SA(b, h) + aoff + m * 2048 + k * 1024); } while (0)
; #define PG8_LDB(dst, b, h) do { _Pragma("unroll") for (int n = 0; n < 2; ++n) _Pragma("unroll") for (int k = 0; k < 2; ++k) dst[n][k] = *(const PG8_LAS bf16x8*)(lds + PG8_SB(b, h) + boff + n * 2048 + k * 1024); } while (0)
; #define PG8_MMA(ai, bj, At, Bt) do { __builtin_amdgcn_s_setprio(1); _Pragma("unroll") for (int m = 0; m < 4; ++m) _Pragma("unroll") for (int n = 0; n < 2; ++n) _Pragma("unroll") for (int k = 0; k < 2; ++k) \
;         acc[ai][bj][m][n] = __builtin_amdgcn_mfma_f32_16x16x32_bf16(Bt[n][k], At[m][k], acc[ai][bj][m][n], 0, 0, 0); __builtin_amdgcn_s_setprio(0); } while (0)
; #define PG8_WAIT_V(n) asm volatile("s_waitcnt vmcnt(" #n ")" ::: "memory")
; #define PG8_WAIT_L(n) asm volatile("s_waitcnt lgkmcnt(" #n ")" ::: "memory")
; #define PG8_BAR __builtin_amdgcn_s_barrier()
; #define PG8_SCHED __builtin_amdgcn_sched_barrier(0)
; template <class Epi, class Sched, bool ALIGN_EPI = false, bool SP2 = false>
; __device__ __forceinline__ void gemm_phase(PG8_LAS unsigned char* lds, const Gemm g, const Sched& S, const Epi& E, const int wv) {
;     ...
;             PG8_WAIT_V(8); PG8_WAIT_L(0); PG8_BAR; PG8_MMA(1, 0, At, B0); PG8_MMA(1, 1, At, B1); PG8_BAR; PG8_SCHED;
;             PG8_LDB(B0, 1, 0); PG8_LDB(B1, 1, 1); PG8_SCHED; PG8_LDA(At, 1, 0); PG8_STAGE(PG8_SA(0, 1), a2 + hstep, voffA);
;             PG8_WAIT_V(8); PG8_WAIT_L(0); PG8_BAR; PG8_MMA(0, 0, At, B0); PG8_MMA(0, 1, At, B1); PG8_BAR; PG8_SCHED;
	s_waitcnt lgkmcnt(0)
	v_mfma_f32_16x16x32_bf16 v[62:65], v[140:143], v[178:181], v[62:65]
	v_mfma_f32_16x16x32_bf16 v[54:57], v[148:151], v[178:181], v[54:57]
	v_mfma_f32_16x16x32_bf16 v[46:49], v[140:143], v[186:189], v[46:49]
	v_mfma_f32_16x16x32_bf16 v[38:41], v[148:151], v[186:189], v[38:41]
	v_mfma_f32_16x16x32_bf16 v[30:33], v[140:143], v[194:197], v[30:33]
	v_mfma_f32_16x16x32_bf16 v[22:25], v[148:151], v[194:197], v[22:25]
	v_mfma_f32_16x16x32_bf16 v[14:17], v[140:143], v[202:205], v[14:17]
	v_mfma_f32_16x16x32_bf16 v[6:9], v[148:151], v[202:205], v[6:9]
	v_mfma_f32_16x16x32_bf16 v[62:65], v[144:147], v[182:185], v[62:65]
	v_mfma_f32_16x16x32_bf16 v[54:57], v[152:155], v[182:185], v[54:57]
	v_mfma_f32_16x16x32_bf16 v[46:49], v[144:147], v[190:193], v[46:49]
	v_mfma_f32_16x16x32_bf16 v[38:41], v[152:155], v[190:193], v[38:41]
	v_mfma_f32_16x16x32_bf16 v[30:33], v[144:147], v[198:201], v[30:33]
	v_mfma_f32_16x16x32_bf16 v[22:25], v[152:155], v[198:201], v[22:25]
	v_mfma_f32_16x16x32_bf16 v[14:17], v[144:147], v[206:209], v[14:17]
	v_mfma_f32_16x16x32_bf16 v[6:9], v[152:155], v[206:209], v[6:9]
	s_setprio 0
	s_setprio 1
	v_mfma_f32_16x16x32_bf16 v[58:61], v[156:159], v[178:181], v[58:61]
	v_mfma_f32_16x16x32_bf16 v[50:53], v[170:173], v[178:181], v[50:53]
	v_mfma_f32_16x16x32_bf16 v[42:45], v[156:159], v[186:189], v[42:45]
	v_mfma_f32_16x16x32_bf16 v[34:37], v[170:173], v[186:189], v[34:37]
	v_mfma_f32_16x16x32_bf16 v[26:29], v[156:159], v[194:197], v[26:29]
	v_mfma_f32_16x16x32_bf16 v[18:21], v[170:173], v[194:197], v[18:21]
	v_mfma_f32_16x16x32_bf16 v[10:13], v[156:159], v[202:205], v[10:13]
	v_mfma_f32_16x16x32_bf16 v[2:5], v[170:173], v[202:205], v[2:5]
	v_mfma_f32_16x16x32_bf16 v[58:61], v[160:163], v[182:185], v[58:61]
	v_mfma_f32_16x16x32_bf16 v[50:53], v[174:177], v[182:185], v[50:53]
	v_mfma_f32_16x16x32_bf16 v[42:45], v[160:163], v[190:193], v[42:45]
	v_mfma_f32_16x16x32_bf16 v[34:37], v[174:177], v[190:193], v[34:37]
	v_mfma_f32_16x16x32_bf16 v[26:29], v[160:163], v[198:201], v[26:29]
	v_mfma_f32_16x16x32_bf16 v[18:21], v[174:177], v[198:201], v[18:21]
	v_mfma_f32_16x16x32_bf16 v[10:13], v[160:163], v[206:209], v[10:13]
	v_mfma_f32_16x16x32_bf16 v[2:5], v[174:177], v[206:209], v[2:5]
	s_barrier
	s_add_i32 s46, 0, 0x18000
	s_add_i32 s47, 0, 0x1c000
	v_add_u32_e32 v152, s46, v166
	v_add_u32_e32 v164, s47, v166
	ds_read_b128 v[140:143], v152
	ds_read_b128 v[144:147], v152 offset:1024
	ds_read_b128 v[148:151], v152 offset:2048
	ds_read_b128 v[152:155], v152 offset:3072
	ds_read_b128 v[156:159], v164
	ds_read_b128 v[160:163], v164 offset:1024
	ds_read_b128 v[170:173], v164 offset:2048
	ds_read_b128 v[174:177], v164 offset:3072
	s_setprio 0
	s_add_u32 s22, s22, 0x40000
	s_addc_u32 s23, s23, 0
	s_mov_b32 m0, s36
	v_lshl_add_u64 v[218:219], s[22:23], 0, v[134:135]
	ds_read_b128 v[178:181], v168 offset:32768
	ds_read_b128 v[182:185], v168 offset:33792
	ds_read_b128 v[186:189], v168 offset:34816
	ds_read_b128 v[190:193], v168 offset:35840
	ds_read_b128 v[194:197], v168 offset:36864
	ds_read_b128 v[198:201], v168 offset:37888
	ds_read_b128 v[202:205], v168 offset:38912
	ds_read_b128 v[206:209], v168 offset:39936
	global_load_lds_dwordx4 v[218:219], off
	v_lshl_add_u64 v[218:219], s[22:23], 0, v[132:133]
	s_mov_b32 m0, s37
	s_nop 0
	global_load_lds_dwordx4 v[218:219], off
	s_waitcnt vmcnt(8)
	s_waitcnt lgkmcnt(0)
	s_setprio 1
	s_barrier
	s_waitcnt lgkmcnt(0)
	v_mfma_f32_16x16x32_bf16 v[126:129], v[140:143], v[178:181], v[126:129]
	v_mfma_f32_16x16x32_bf16 v[118:121], v[148:151], v[178:181], v[118:121]
	v_mfma_f32_16x16x32_bf16 v[110:113], v[140:143], v[186:189], v[110:113]
	v_mfma_f32_16x16x32_bf16 v[102:105], v[148:151], v[186:189], v[102:105]
	v_mfma_f32_16x16x32_bf16 v[94:97], v[140:143], v[194:197], v[94:97]
	v_mfma_f32_16x16x32_bf16 v[86:89], v[148:151], v[194:197], v[86:89]
	v_mfma_f32_16x16x32_bf16 v[78:81], v[140:143], v[202:205], v[78:81]
	v_mfma_f32_16x16x32_bf16 v[70:73], v[148:151], v[202:205], v[70:73]
	v_mfma_f32_16x16x32_bf16 v[126:129], v[144:147], v[182:185], v[126:129]
	v_mfma_f32_16x16x32_bf16 v[118:121], v[152:155], v[182:185], v[118:121]
	v_mfma_f32_16x16x32_bf16 v[110:113], v[144:147], v[190:193], v[110:113]
	v_mfma_f32_16x16x32_bf16 v[102:105], v[152:155], v[190:193], v[102:105]
	v_mfma_f32_16x16x32_bf16 v[94:97], v[144:147], v[198:201], v[94:97]
	v_mfma_f32_16x16x32_bf16 v[86:89], v[152:155], v[198:201], v[86:89]
	v_mfma_f32_16x16x32_bf16 v[78:81], v[144:147], v[206:209], v[78:81]
	v_mfma_f32_16x16x32_bf16 v[70:73], v[152:155], v[206:209], v[70:73]
	s_setprio 0
	s_setprio 1
	v_mfma_f32_16x16x32_bf16 v[122:125], v[156:159], v[178:181], v[122:125]
	v_mfma_f32_16x16x32_bf16 v[114:117], v[170:173], v[178:181], v[114:117]
	v_mfma_f32_16x16x32_bf16 v[106:109], v[156:159], v[186:189], v[106:109]
	v_mfma_f32_16x16x32_bf16 v[98:101], v[170:173], v[186:189], v[98:101]
	v_mfma_f32_16x16x32_bf16 v[90:93], v[156:159], v[194:197], v[90:93]
	v_mfma_f32_16x16x32_bf16 v[82:85], v[170:173], v[194:197], v[82:85]
	v_mfma_f32_16x16x32_bf16 v[74:77], v[156:159], v[202:205], v[74:77]
	v_mfma_f32_16x16x32_bf16 v[66:69], v[170:173], v[202:205], v[66:69]
	v_mfma_f32_16x16x32_bf16 v[122:125], v[160:163], v[182:185], v[122:125]
	v_mfma_f32_16x16x32_bf16 v[114:117], v[174:177], v[182:185], v[114:117]
	v_mfma_f32_16x16x32_bf16 v[106:109], v[160:163], v[190:193], v[106:109]
	v_mfma_f32_16x16x32_bf16 v[98:101], v[174:177], v[190:193], v[98:101]
	v_mfma_f32_16x16x32_bf16 v[90:93], v[160:163], v[198:201], v[90:93]
	v_mfma_f32_16x16x32_bf16 v[82:85], v[174:177], v[198:201], v[82:85]
	v_mfma_f32_16x16x32_bf16 v[74:77], v[160:163], v[206:209], v[74:77]
	v_mfma_f32_16x16x32_bf16 v[66:69], v[174:177], v[206:209], v[66:69]
	s_barrier
; #define PG8_STAGE(bufoff, gbase, voff) do { _Pragma("unroll") for (int _i = 0; _i < 2; ++_i) \
;         __builtin_amdgcn_global_load_lds((const unsigned*)((const char*)(gbase) + (voff)[_i]), (PG8_LAS unsigned*)(lds + (bufoff) + ldsw + _i * 8192), 16, 0, 0); } while (0)
; #define PG8_LDA(dst, b, h) do { _Pragma("unroll") for (int m = 0; m < 4; ++m) _Pragma("unroll") for (int k = 0; k < 2; ++k) dst[m][k] = *(const PG8_LAS bf16x8*)(lds + PG8_SA(b, h) + aoff + m * 2048 + k * 1024); } while (0)
; #define PG8_MMA(ai, bj, At, Bt) do { __builtin_amdgcn_s_setprio(1); _Pragma("unroll") for (int m = 0; m < 4; ++m) _Pragma("unroll") for (int n = 0; n < 2; ++n) _Pragma("unroll") for (int k = 0; k < 2; ++k) \
;         acc[ai][bj][m][n] = __builtin_amdgcn_mfma_f32_16x16x32_bf16(Bt[n][k], At[m][k], acc[ai][bj][m][n], 0, 0, 0); __builtin_amdgcn_s_setprio(0); } while (0)
; #define PG8_WAIT_V(n) asm volatile("s_waitcnt vmcnt(" #n ")" ::: "memory")
; #define PG8_WAIT_L(n) asm volatile("s_waitcnt lgkmcnt(" #n ")" ::: "memory")
; #define PG8_BAR __builtin_amdgcn_s_barrier()
; #define PG8_SCHED __builtin_amdgcn_sched_barrier(0)
; template <class Epi, class Sched, bool ALIGN_EPI = false, bool SP2 = false>
; __device__ __forceinline__ void gemm_phase(PG8_LAS unsigned char* lds, const Gemm g, const Sched& S, const Epi& E, const int wv) {
;     ...
;             PG8_LDA(At, 1, 1); PG8_STAGE(PG8_SB(1, 0), b3, voffB); PG8_STAGE(PG8_SB(1, 1), b3 + hstep, voffB); PG8_STAGE(PG8_SA(1, 0), a3, voffA);
;             PG8_WAIT_V(8); PG8_WAIT_L(0); PG8_BAR; PG8_MMA(1, 0, At, B0); PG8_MMA(1, 1, At, B1); PG8_BAR; PG8_SCHED;
	s_add_i32 s22, s46, s29
	v_lshl_add_u64 v[210:211], v[210:211], 0, s[2:3]
	s_mov_b32 m0, s22
	ds_read_b128 v[178:181], v168 offset:49152
	ds_read_b128 v[182:185], v168 offset:50176
	ds_read_b128 v[186:189], v168 offset:51200
	ds_read_b128 v[190:193], v168 offset:52224
	ds_read_b128 v[194:197], v168 offset:53248
	ds_read_b128 v[198:201], v168 offset:54272
	ds_read_b128 v[202:205], v168 offset:55296
	ds_read_b128 v[206:209], v168 offset:56320
	s_setprio 0
	global_load_lds_dwordx4 v[210:211], off
	s_add_i32 m0, s22, 0x2000
	s_add_u32 s20, s20, 0x40080
	v_lshl_add_u64 v[210:211], v[212:213], 0, s[2:3]
	s_addc_u32 s21, s21, 0
	s_add_i32 s22, s47, s29
	global_load_lds_dwordx4 v[210:211], off
	v_lshl_add_u64 v[210:211], s[20:21], 0, v[0:1]
	s_mov_b32 m0, s22
	s_nop 0
	global_load_lds_dwordx4 v[210:211], off
	v_lshl_add_u64 v[210:211], s[20:21], 0, v[130:131]
	s_add_i32 m0, s22, 0x2000
	s_nop 0
	global_load_lds_dwordx4 v[210:211], off
	v_lshl_add_u64 v[210:211], v[214:215], 0, s[2:3]
	s_mov_b32 m0, s39
	s_nop 0
	global_load_lds_dwordx4 v[210:211], off
	v_lshl_add_u64 v[210:211], v[216:217], 0, s[2:3]
	s_mov_b32 m0, s40
	s_nop 0
	global_load_lds_dwordx4 v[210:211], off
	s_waitcnt vmcnt(8)
	s_waitcnt lgkmcnt(0)
	s_setprio 1
	s_barrier
	s_waitcnt lgkmcnt(0)
	v_mfma_f32_16x16x32_bf16 v[62:65], v[140:143], v[178:181], v[62:65]
	v_mfma_f32_16x16x32_bf16 v[54:57], v[148:151], v[178:181], v[54:57]
	v_mfma_f32_16x16x32_bf16 v[46:49], v[140:143], v[186:189], v[46:49]
	v_mfma_f32_16x16x32_bf16 v[38:41], v[148:151], v[186:189], v[38:41]
	v_mfma_f32_16x16x32_bf16 v[30:33], v[140:143], v[194:197], v[30:33]
	v_mfma_f32_16x16x32_bf16 v[22:25], v[148:151], v[194:197], v[22:25]
	v_mfma_f32_16x16x32_bf16 v[14:17], v[140:143], v[202:205], v[14:17]
	v_mfma_f32_16x16x32_bf16 v[6:9], v[148:151], v[202:205], v[6:9]
	v_mfma_f32_16x16x32_bf16 v[62:65], v[144:147], v[182:185], v[62:65]
	v_mfma_f32_16x16x32_bf16 v[54:57], v[152:155], v[182:185], v[54:57]
	v_mfma_f32_16x16x32_bf16 v[46:49], v[144:147], v[190:193], v[46:49]
	v_mfma_f32_16x16x32_bf16 v[38:41], v[152:155], v[190:193], v[38:41]
	v_mfma_f32_16x16x32_bf16 v[30:33], v[144:147], v[198:201], v[30:33]
	v_mfma_f32_16x16x32_bf16 v[22:25], v[152:155], v[198:201], v[22:25]
	v_mfma_f32_16x16x32_bf16 v[14:17], v[144:147], v[206:209], v[14:17]
	v_mfma_f32_16x16x32_bf16 v[6:9], v[152:155], v[206:209], v[6:9]
	s_setprio 0
	s_setprio 1
	v_mfma_f32_16x16x32_bf16 v[58:61], v[156:159], v[178:181], v[58:61]
	v_mfma_f32_16x16x32_bf16 v[50:53], v[170:173], v[178:181], v[50:53]
	v_mfma_f32_16x16x32_bf16 v[42:45], v[156:159], v[186:189], v[42:45]
	v_mfma_f32_16x16x32_bf16 v[34:37], v[170:173], v[186:189], v[34:37]
	v_mfma_f32_16x16x32_bf16 v[26:29], v[156:159], v[194:197], v[26:29]
	v_mfma_f32_16x16x32_bf16 v[18:21], v[170:173], v[194:197], v[18:21]
	v_mfma_f32_16x16x32_bf16 v[10:13], v[156:159], v[202:205], v[10:13]
	v_mfma_f32_16x16x32_bf16 v[2:5], v[170:173], v[202:205], v[2:5]
	v_mfma_f32_16x16x32_bf16 v[58:61], v[160:163], v[182:185], v[58:61]
	v_mfma_f32_16x16x32_bf16 v[50:53], v[174:177], v[182:185], v[50:53]
	v_mfma_f32_16x16x32_bf16 v[42:45], v[160:163], v[190:193], v[42:45]
	v_mfma_f32_16x16x32_bf16 v[34:37], v[174:177], v[190:193], v[34:37]
	v_mfma_f32_16x16x32_bf16 v[26:29], v[160:163], v[198:201], v[26:29]
	v_mfma_f32_16x16x32_bf16 v[18:21], v[174:177], v[198:201], v[18:21]
	v_mfma_f32_16x16x32_bf16 v[10:13], v[160:163], v[206:209], v[10:13]
	v_mfma_f32_16x16x32_bf16 v[2:5], v[174:177], v[206:209], v[2:5]
	s_barrier
	s_setprio 0
	s_add_i32 s45, s45, 2
	s_add_u32 s18, s18, 0x100
	s_addc_u32 s19, s19, 0
	s_add_u32 s43, s43, 0x100
	s_addc_u32 s44, s44, 0
	s_cmp_gt_u32 s45, 13
	s_cbranch_scc0 .LBB0_428
	s_and_b64 vcc, exec, s[6:7]
	s_cbranch_vccz .LBB0_431
	s_barrier

; #define PG8_STAGE(bufoff, gbase, voff) do { _Pragma("unroll") for (int _i = 0; _i < 2; ++_i) \
;         __builtin_amdgcn_global_load_lds((const unsigned*)((const char*)(gbase) + (voff)[_i]), (PG8_LAS unsigned*)(lds + (bufoff) + ldsw + _i * 8192), 16, 0, 0); } while (0)
; #define PG8_LDA(dst, b, h) do { _Pragma("unroll") for (int m = 0; m < 4; ++m) _Pragma("unroll") for (int k = 0; k < 2; ++k) dst[m][k] = *(const PG8_LAS bf16x8*)(lds + PG8_SA(b, h) + aoff + m * 2048 + k * 1024); } while (0)
; #define PG8_LDB(dst, b, h) do { _Pragma("unroll") for (int n = 0; n < 2; ++n) _Pragma("unroll") for (int k = 0; k < 2; ++k) dst[n][k] = *(const PG8_LAS bf16x8*)(lds + PG8_SB(b, h) + boff + n * 2048 + k * 1024); } while (0)
; #define PG8_MMA(ai, bj, At, Bt) do { __builtin_amdgcn_s_setprio(1); _Pragma("unroll") for (int m = 0; m < 4; ++m) _Pragma("unroll") for (int n = 0; n < 2; ++n) _Pragma("unroll") for (int k = 0; k < 2; ++k) \
;         acc[ai][bj][m][n] = __builtin_amdgcn_mfma_f32_16x16x32_bf16(Bt[n][k], At[m][k], acc[ai][bj][m][n], 0, 0, 0); __builtin_amdgcn_s_setprio(0); } while (0)
; #define PG8_WAIT_V(n) asm volatile("s_waitcnt vmcnt(" #n ")" ::: "memory")
; #define PG8_WAIT_L(n) asm volatile("s_waitcnt lgkmcnt(" #n ")" ::: "memory")
; #define PG8_BAR __builtin_amdgcn_s_barrier()
; #define PG8_SCHED __builtin_amdgcn_sched_barrier(0)
; template <class Epi, class Sched, bool ALIGN_EPI = false, bool SP2 = false>
; __device__ __forceinline__ void gemm_phase(PG8_LAS unsigned char* lds, const Gemm g, const Sched& S, const Epi& E, const int wv) {
;     ...
;             const bool last = (t == nt - 2);
;             const char* a1 = cA + (size_t)(t + 1) * kstep;
;             const char* a2 = last ? nA : cA + (size_t)(t + 2) * kstep; const char* b2 = last ? nB : cB + (size_t)(t + 2) * kstep;
;             const char* a3 = a2 + kstep; const char* b3 = b2 + kstep;
;             if (last && has_next) S.a_ready(nxt);
;             if constexpr (SP2) {
;             PG8_LDB(B0, 0, 0); PG8_LDB(B1, 0, 1); PG8_SCHED; PG8_LDA(At, 0, 0); PG8_STAGE(PG8_SA(1, 1), a1 + hstep, voffA);
;             PG8_WAIT_V(8); PG8_WAIT_L(0); PG8_BAR; PG8_MMA(0, 0, At, B0); PG8_MMA(0, 1, At, B1); PG8_BAR; PG8_SCHED;
;             PG8_LDA(At, 0, 1); PG8_STAGE(PG8_SB(0, 0), b2, voffB); PG8_STAGE(PG8_SB(0, 1), b2 + hstep, voffB); PG8_STAGE(PG8_SA(0, 0), a2, voffA);
.LBB0_504:
	s_add_u32 s10, s8, 0x100
	s_addc_u32 s11, s9, 0
	s_add_i32 s52, 0, 0x10000
	s_cmp_eq_u32 s51, 40
	s_cselect_b32 s29, s1, s11
	s_cselect_b32 s28, s0, s10
	s_cselect_b32 s27, s25, s50
	s_cselect_b32 s26, s24, s49
	s_add_i32 s53, 0, 0x14000
	v_add_u32_e32 v142, s52, v187
	v_add_u32_e32 v168, s53, v187
	ds_read_b128 v[122:125], v142
	ds_read_b128 v[130:133], v142 offset:1024
	ds_read_b128 v[138:141], v142 offset:2048
	ds_read_b128 v[142:145], v142 offset:3072
	ds_read_b128 v[146:149], v168
	ds_read_b128 v[150:153], v168 offset:1024
	ds_read_b128 v[154:157], v168 offset:2048
	ds_read_b128 v[168:171], v168 offset:3072
	v_lshl_add_u64 v[184:185], s[8:9], 0, v[164:165]
	s_add_i32 m0, s37, 0xc000
	ds_read_b128 v[172:175], v189
	ds_read_b128 v[176:179], v189 offset:1024
	ds_read_b128 v[180:183], v189 offset:2048
	ds_read_b128 v[190:193], v189 offset:3072
	ds_read_b128 v[194:197], v189 offset:4096
	ds_read_b128 v[198:201], v189 offset:5120
	ds_read_b128 v[202:205], v189 offset:6144
	ds_read_b128 v[206:209], v189 offset:7168
	global_load_lds_dwordx4 v[184:185], off
	v_lshl_add_u64 v[184:185], s[8:9], 0, v[166:167]
	s_add_i32 m0, s37, 0xe000
	s_nop 0
	global_load_lds_dwordx4 v[184:185], off
	s_waitcnt vmcnt(8)
	s_waitcnt lgkmcnt(0)
	s_setprio 1
	s_barrier
	s_waitcnt lgkmcnt(0)
	v_mfma_f32_16x16x32_bf16 v[134:137], v[122:125], v[172:175], v[134:137]
	v_mfma_f32_16x16x32_bf16 v[126:129], v[138:141], v[172:175], v[126:129]
	v_mfma_f32_16x16x32_bf16 v[110:113], v[122:125], v[180:183], v[110:113]
	v_mfma_f32_16x16x32_bf16 v[106:109], v[138:141], v[180:183], v[106:109]
	v_mfma_f32_16x16x32_bf16 v[94:97], v[122:125], v[194:197], v[94:97]
	v_mfma_f32_16x16x32_bf16 v[90:93], v[138:141], v[194:197], v[90:93]
	v_mfma_f32_16x16x32_bf16 v[78:81], v[122:125], v[202:205], v[78:81]
	v_mfma_f32_16x16x32_bf16 v[74:77], v[138:141], v[202:205], v[74:77]
	v_mfma_f32_16x16x32_bf16 v[134:137], v[130:133], v[176:179], v[134:137]
	v_mfma_f32_16x16x32_bf16 v[126:129], v[142:145], v[176:179], v[126:129]
	v_mfma_f32_16x16x32_bf16 v[110:113], v[130:133], v[190:193], v[110:113]
	v_mfma_f32_16x16x32_bf16 v[106:109], v[142:145], v[190:193], v[106:109]
	v_mfma_f32_16x16x32_bf16 v[94:97], v[130:133], v[198:201], v[94:97]
	v_mfma_f32_16x16x32_bf16 v[90:93], v[142:145], v[198:201], v[90:93]
	v_mfma_f32_16x16x32_bf16 v[78:81], v[130:133], v[206:209], v[78:81]
	v_mfma_f32_16x16x32_bf16 v[74:77], v[142:145], v[206:209], v[74:77]
	s_setprio 0
	s_setprio 1
	v_mfma_f32_16x16x32_bf16 v[118:121], v[146:149], v[172:175], v[118:121]
	v_mfma_f32_16x16x32_bf16 v[114:117], v[154:157], v[172:175], v[114:117]
	v_mfma_f32_16x16x32_bf16 v[102:105], v[146:149], v[180:183], v[102:105]
	v_mfma_f32_16x16x32_bf16 v[98:101], v[154:157], v[180:183], v[98:101]
	v_mfma_f32_16x16x32_bf16 v[86:89], v[146:149], v[194:197], v[86:89]
	v_mfma_f32_16x16x32_bf16 v[82:85], v[154:157], v[194:197], v[82:85]
	v_mfma_f32_16x16x32_bf16 v[70:73], v[146:149], v[202:205], v[70:73]
	v_mfma_f32_16x16x32_bf16 v[66:69], v[154:157], v[202:205], v[66:69]
	v_mfma_f32_16x16x32_bf16 v[118:121], v[150:153], v[176:179], v[118:121]
	v_mfma_f32_16x16x32_bf16 v[114:117], v[168:171], v[176:179], v[114:117]
	v_mfma_f32_16x16x32_bf16 v[102:105], v[150:153], v[190:193], v[102:105]
	v_mfma_f32_16x16x32_bf16 v[98:101], v[168:171], v[190:193], v[98:101]
	v_mfma_f32_16x16x32_bf16 v[86:89], v[150:153], v[198:201], v[86:89]
	v_mfma_f32_16x16x32_bf16 v[82:85], v[168:171], v[198:201], v[82:85]
	v_mfma_f32_16x16x32_bf16 v[70:73], v[150:153], v[206:209], v[70:73]
	v_mfma_f32_16x16x32_bf16 v[66:69], v[168:171], v[206:209], v[66:69]
	s_barrier
	s_add_i32 s8, s52, s36
	v_lshl_add_u64 v[184:185], s[26:27], 0, v[0:1]
	s_mov_b32 m0, s8
	ds_read_b128 v[172:175], v189 offset:16384
	ds_read_b128 v[176:179], v189 offset:17408
	ds_read_b128 v[180:183], v189 offset:18432
	ds_read_b128 v[190:193], v189 offset:19456
	ds_read_b128 v[194:197], v189 offset:20480
	ds_read_b128 v[198:201], v189 offset:21504
	ds_read_b128 v[202:205], v189 offset:22528
	ds_read_b128 v[206:209], v189 offset:23552
	s_setprio 0
	global_load_lds_dwordx4 v[184:185], off
	s_add_i32 m0, s8, 0x2000
	s_add_u32 s8, s26, 0xb0000
	v_lshl_add_u64 v[210:211], s[26:27], 0, v[162:163]
	s_addc_u32 s9, s27, 0
	s_add_i32 s52, s53, s36
	global_load_lds_dwordx4 v[210:211], off
	v_lshl_add_u64 v[212:213], s[8:9], 0, v[0:1]
	s_mov_b32 m0, s52
	v_lshl_add_u64 v[214:215], s[28:29], 0, v[160:161]
	global_load_lds_dwordx4 v[212:213], off
	v_lshl_add_u64 v[212:213], s[8:9], 0, v[162:163]
	s_add_i32 m0, s52, 0x2000
	s_nop 0
	global_load_lds_dwordx4 v[212:213], off
	v_lshl_add_u64 v[212:213], s[28:29], 0, v[158:159]
	s_mov_b32 m0, s37
	s_nop 0
	global_load_lds_dwordx4 v[212:213], off
	s_mov_b32 m0, s38
	s_nop 0
	global_load_lds_dwordx4 v[214:215], off
	s_waitcnt vmcnt(8)
	s_waitcnt lgkmcnt(0)
	s_setprio 1
	s_barrier
; #define PG8_STAGE(bufoff, gbase, voff) do { _Pragma("unroll") for (int _i = 0; _i < 2; ++_i) \
;         __builtin_amdgcn_global_load_lds((const unsigned*)((const char*)(gbase) + (voff)[_i]), (PG8_LAS unsigned*)(lds + (bufoff) + ldsw + _i * 8192), 16, 0, 0); } while (0)
; #define PG8_LDA(dst, b, h) do { _Pragma("unroll") for (int m = 0; m < 4; ++m) _Pragma("unroll") for (int k = 0; k < 2; ++k) dst[m][k] = *(const PG8_LAS bf16x8*)(lds + PG8_SA(b, h) + aoff + m * 2048 + k * 1024); } while (0)
; #define PG8_LDB(dst, b, h) do { _Pragma("unroll") for (int n = 0; n < 2; ++n) _Pragma("unroll") for (int k = 0; k < 2; ++k) dst[n][k] = *(const PG8_LAS bf16x8*)(lds + PG8_SB(b, h) + boff + n * 2048 + k * 1024); } while (0)
; #define PG8_MMA(ai, bj, At, Bt) do { __builtin_amdgcn_s_setprio(1); _Pragma("unroll") for (int m = 0; m < 4; ++m) _Pragma("unroll") for (int n = 0; n < 2; ++n) _Pragma("unroll") for (int k = 0; k < 2; ++k) \
;         acc[ai][bj][m][n] = __builtin_amdgcn_mfma_f32_16x16x32_bf16(Bt[n][k], At[m][k], acc[ai][bj][m][n], 0, 0, 0); __builtin_amdgcn_s_setprio(0); } while (0)
; #define PG8_WAIT_V(n) asm volatile("s_waitcnt vmcnt(" #n ")" ::: "memory")
; #define PG8_WAIT_L(n) asm volatile("s_waitcnt lgkmcnt(" #n ")" ::: "memory")
; #define PG8_BAR __builtin_amdgcn_s_barrier()
; #define PG8_SCHED __builtin_amdgcn_sched_barrier(0)
; template <class Epi, class Sched, bool ALIGN_EPI = false, bool SP2 = false>
; __device__ __forceinline__ void gemm_phase(PG8_LAS unsigned char* lds, const Gemm g, const Sched& S, const Epi& E, const int wv) {
;     ...
;             PG8_WAIT_V(8); PG8_WAIT_L(0); PG8_BAR; PG8_MMA(1, 0, At, B0); PG8_MMA(1, 1, At, B1); PG8_BAR; PG8_SCHED;
;             PG8_LDB(B0, 1, 0); PG8_LDB(B1, 1, 1); PG8_SCHED; PG8_LDA(At, 1, 0); PG8_STAGE(PG8_SA(0, 1), a2 + hstep, voffA);
;             PG8_WAIT_V(8); PG8_WAIT_L(0); PG8_BAR; PG8_MMA(0, 0, At, B0); PG8_MMA(0, 1, At, B1); PG8_BAR; PG8_SCHED;
	s_waitcnt lgkmcnt(0)
	v_mfma_f32_16x16x32_bf16 v[62:65], v[122:125], v[172:175], v[62:65]
	v_mfma_f32_16x16x32_bf16 v[58:61], v[138:141], v[172:175], v[58:61]
	v_mfma_f32_16x16x32_bf16 v[46:49], v[122:125], v[180:183], v[46:49]
	v_mfma_f32_16x16x32_bf16 v[42:45], v[138:141], v[180:183], v[42:45]
	v_mfma_f32_16x16x32_bf16 v[30:33], v[122:125], v[194:197], v[30:33]
	v_mfma_f32_16x16x32_bf16 v[26:29], v[138:141], v[194:197], v[26:29]
	v_mfma_f32_16x16x32_bf16 v[14:17], v[122:125], v[202:205], v[14:17]
	v_mfma_f32_16x16x32_bf16 v[10:13], v[138:141], v[202:205], v[10:13]
	v_mfma_f32_16x16x32_bf16 v[62:65], v[130:133], v[176:179], v[62:65]
	v_mfma_f32_16x16x32_bf16 v[58:61], v[142:145], v[176:179], v[58:61]
	v_mfma_f32_16x16x32_bf16 v[46:49], v[130:133], v[190:193], v[46:49]
	v_mfma_f32_16x16x32_bf16 v[42:45], v[142:145], v[190:193], v[42:45]
	v_mfma_f32_16x16x32_bf16 v[30:33], v[130:133], v[198:201], v[30:33]
	v_mfma_f32_16x16x32_bf16 v[26:29], v[142:145], v[198:201], v[26:29]
	v_mfma_f32_16x16x32_bf16 v[14:17], v[130:133], v[206:209], v[14:17]
	v_mfma_f32_16x16x32_bf16 v[10:13], v[142:145], v[206:209], v[10:13]
	s_setprio 0
	s_setprio 1
	v_mfma_f32_16x16x32_bf16 v[54:57], v[146:149], v[172:175], v[54:57]
	v_mfma_f32_16x16x32_bf16 v[50:53], v[154:157], v[172:175], v[50:53]
	v_mfma_f32_16x16x32_bf16 v[38:41], v[146:149], v[180:183], v[38:41]
	v_mfma_f32_16x16x32_bf16 v[34:37], v[154:157], v[180:183], v[34:37]
	v_mfma_f32_16x16x32_bf16 v[22:25], v[146:149], v[194:197], v[22:25]
	v_mfma_f32_16x16x32_bf16 v[18:21], v[154:157], v[194:197], v[18:21]
	v_mfma_f32_16x16x32_bf16 v[6:9], v[146:149], v[202:205], v[6:9]
	v_mfma_f32_16x16x32_bf16 v[2:5], v[154:157], v[202:205], v[2:5]
	v_mfma_f32_16x16x32_bf16 v[54:57], v[150:153], v[176:179], v[54:57]
	v_mfma_f32_16x16x32_bf16 v[50:53], v[168:171], v[176:179], v[50:53]
	v_mfma_f32_16x16x32_bf16 v[38:41], v[150:153], v[190:193], v[38:41]
	v_mfma_f32_16x16x32_bf16 v[34:37], v[168:171], v[190:193], v[34:37]
	v_mfma_f32_16x16x32_bf16 v[22:25], v[150:153], v[198:201], v[22:25]
	v_mfma_f32_16x16x32_bf16 v[18:21], v[168:171], v[198:201], v[18:21]
	v_mfma_f32_16x16x32_bf16 v[6:9], v[150:153], v[206:209], v[6:9]
	v_mfma_f32_16x16x32_bf16 v[2:5], v[168:171], v[206:209], v[2:5]
	s_barrier
	s_add_i32 s52, 0, 0x18000
	s_add_i32 s53, 0, 0x1c000
	v_add_u32_e32 v142, s52, v187
	v_add_u32_e32 v168, s53, v187
	ds_read_b128 v[122:125], v142
	ds_read_b128 v[130:133], v142 offset:1024
	ds_read_b128 v[138:141], v142 offset:2048
	ds_read_b128 v[142:145], v142 offset:3072
	ds_read_b128 v[146:149], v168
	ds_read_b128 v[150:153], v168 offset:1024
	ds_read_b128 v[154:157], v168 offset:2048
	ds_read_b128 v[168:171], v168 offset:3072
	s_setprio 0
	s_add_u32 s8, s28, 0xb0000
	s_addc_u32 s9, s29, 0
	s_mov_b32 m0, s39
	v_lshl_add_u64 v[216:217], s[8:9], 0, v[158:159]
	ds_read_b128 v[172:175], v189 offset:32768
	ds_read_b128 v[176:179], v189 offset:33792
	ds_read_b128 v[180:183], v189 offset:34816
	ds_read_b128 v[190:193], v189 offset:35840
	ds_read_b128 v[194:197], v189 offset:36864
	ds_read_b128 v[198:201], v189 offset:37888
	ds_read_b128 v[202:205], v189 offset:38912
	ds_read_b128 v[206:209], v189 offset:39936
	global_load_lds_dwordx4 v[216:217], off
	v_lshl_add_u64 v[216:217], s[8:9], 0, v[160:161]
	s_mov_b32 m0, s40
	s_nop 0
	global_load_lds_dwordx4 v[216:217], off
	s_waitcnt vmcnt(8)
	s_waitcnt lgkmcnt(0)
	s_setprio 1
	s_barrier
	s_waitcnt lgkmcnt(0)
	v_mfma_f32_16x16x32_bf16 v[134:137], v[122:125], v[172:175], v[134:137]
	v_mfma_f32_16x16x32_bf16 v[126:129], v[138:141], v[172:175], v[126:129]
	v_mfma_f32_16x16x32_bf16 v[110:113], v[122:125], v[180:183], v[110:113]
	v_mfma_f32_16x16x32_bf16 v[106:109], v[138:141], v[180:183], v[106:109]
	v_mfma_f32_16x16x32_bf16 v[94:97], v[122:125], v[194:197], v[94:97]
	v_mfma_f32_16x16x32_bf16 v[90:93], v[138:141], v[194:197], v[90:93]
	v_mfma_f32_16x16x32_bf16 v[78:81], v[122:125], v[202:205], v[78:81]
	v_mfma_f32_16x16x32_bf16 v[74:77], v[138:141], v[202:205], v[74:77]
	v_mfma_f32_16x16x32_bf16 v[134:137], v[130:133], v[176:179], v[134:137]
	v_mfma_f32_16x16x32_bf16 v[126:129], v[142:145], v[176:179], v[126:129]
	v_mfma_f32_16x16x32_bf16 v[110:113], v[130:133], v[190:193], v[110:113]
	v_mfma_f32_16x16x32_bf16 v[106:109], v[142:145], v[190:193], v[106:109]
	v_mfma_f32_16x16x32_bf16 v[94:97], v[130:133], v[198:201], v[94:97]
	v_mfma_f32_16x16x32_bf16 v[90:93], v[142:145], v[198:201], v[90:93]
	v_mfma_f32_16x16x32_bf16 v[78:81], v[130:133], v[206:209], v[78:81]
	v_mfma_f32_16x16x32_bf16 v[74:77], v[142:145], v[206:209], v[74:77]
	s_setprio 0
	s_setprio 1
	v_mfma_f32_16x16x32_bf16 v[118:121], v[146:149], v[172:175], v[118:121]
	v_mfma_f32_16x16x32_bf16 v[114:117], v[154:157], v[172:175], v[114:117]
	v_mfma_f32_16x16x32_bf16 v[102:105], v[146:149], v[180:183], v[102:105]
	v_mfma_f32_16x16x32_bf16 v[98:101], v[154:157], v[180:183], v[98:101]
	v_mfma_f32_16x16x32_bf16 v[86:89], v[146:149], v[194:197], v[86:89]
	v_mfma_f32_16x16x32_bf16 v[82:85], v[154:157], v[194:197], v[82:85]
	v_mfma_f32_16x16x32_bf16 v[70:73], v[146:149], v[202:205], v[70:73]
	v_mfma_f32_16x16x32_bf16 v[66:69], v[154:157], v[202:205], v[66:69]
	v_mfma_f32_16x16x32_bf16 v[118:121], v[150:153], v[176:179], v[118:121]
	v_mfma_f32_16x16x32_bf16 v[114:117], v[168:171], v[176:179], v[114:117]
	v_mfma_f32_16x16x32_bf16 v[102:105], v[150:153], v[190:193], v[102:105]
	v_mfma_f32_16x16x32_bf16 v[98:101], v[168:171], v[190:193], v[98:101]
	v_mfma_f32_16x16x32_bf16 v[86:89], v[150:153], v[198:201], v[86:89]
	v_mfma_f32_16x16x32_bf16 v[82:85], v[168:171], v[198:201], v[82:85]
	v_mfma_f32_16x16x32_bf16 v[70:73], v[150:153], v[206:209], v[70:73]
	v_mfma_f32_16x16x32_bf16 v[66:69], v[168:171], v[206:209], v[66:69]
	s_barrier
; #define PG8_STAGE(bufoff, gbase, voff) do { _Pragma("unroll") for (int _i = 0; _i < 2; ++_i) \
;         __builtin_amdgcn_global_load_lds((const unsigned*)((const char*)(gbase) + (voff)[_i]), (PG8_LAS unsigned*)(lds + (bufoff) + ldsw + _i * 8192), 16, 0, 0); } while (0)
; #define PG8_LDA(dst, b, h) do { _Pragma("unroll") for (int m = 0; m < 4; ++m) _Pragma("unroll") for (int k = 0; k < 2; ++k) dst[m][k] = *(const PG8_LAS bf16x8*)(lds + PG8_SA(b, h) + aoff + m * 2048 + k * 1024); } while (0)
; #define PG8_MMA(ai, bj, At, Bt) do { __builtin_amdgcn_s_setprio(1); _Pragma("unroll") for (int m = 0; m < 4; ++m) _Pragma("unroll") for (int n = 0; n < 2; ++n) _Pragma("unroll") for (int k = 0; k < 2; ++k) \
;         acc[ai][bj][m][n] = __builtin_amdgcn_mfma_f32_16x16x32_bf16(Bt[n][k], At[m][k], acc[ai][bj][m][n], 0, 0, 0); __builtin_amdgcn_s_setprio(0); } while (0)
; #define PG8_WAIT_V(n) asm volatile("s_waitcnt vmcnt(" #n ")" ::: "memory")
; #define PG8_WAIT_L(n) asm volatile("s_waitcnt lgkmcnt(" #n ")" ::: "memory")
; #define PG8_BAR __builtin_amdgcn_s_barrier()
; #define PG8_SCHED __builtin_amdgcn_sched_barrier(0)
; template <class Epi, class Sched, bool ALIGN_EPI = false, bool SP2 = false>
; __device__ __forceinline__ void gemm_phase(PG8_LAS unsigned char* lds, const Gemm g, const Sched& S, const Epi& E, const int wv) {
;     ...
;             PG8_LDA(At, 1, 1); PG8_STAGE(PG8_SB(1, 0), b3, voffB); PG8_STAGE(PG8_SB(1, 1), b3 + hstep, voffB); PG8_STAGE(PG8_SA(1, 0), a3, voffA);
;             PG8_WAIT_V(8); PG8_WAIT_L(0); PG8_BAR; PG8_MMA(1, 0, At, B0); PG8_MMA(1, 1, At, B1); PG8_BAR; PG8_SCHED;
	s_add_i32 s8, s52, s36
	v_lshl_add_u64 v[184:185], v[184:185], 0, s[2:3]
	s_mov_b32 m0, s8
	ds_read_b128 v[172:175], v189 offset:49152
	ds_read_b128 v[176:179], v189 offset:50176
	ds_read_b128 v[180:183], v189 offset:51200
	ds_read_b128 v[190:193], v189 offset:52224
	ds_read_b128 v[194:197], v189 offset:53248
	ds_read_b128 v[198:201], v189 offset:54272
	ds_read_b128 v[202:205], v189 offset:55296
	ds_read_b128 v[206:209], v189 offset:56320
	s_setprio 0
	global_load_lds_dwordx4 v[184:185], off
	s_add_i32 m0, s8, 0x2000
	s_add_u32 s8, s26, 0xb0080
	v_lshl_add_u64 v[184:185], v[210:211], 0, s[2:3]
	s_addc_u32 s9, s27, 0
	s_add_i32 s26, s53, s36
	global_load_lds_dwordx4 v[184:185], off
	v_lshl_add_u64 v[184:185], s[8:9], 0, v[0:1]
	s_mov_b32 m0, s26
	s_nop 0
	global_load_lds_dwordx4 v[184:185], off
	v_lshl_add_u64 v[184:185], s[8:9], 0, v[162:163]
	s_add_i32 m0, s26, 0x2000
	s_nop 0
	global_load_lds_dwordx4 v[184:185], off
	v_lshl_add_u64 v[184:185], v[212:213], 0, s[2:3]
	s_mov_b32 m0, s42
	s_nop 0
	global_load_lds_dwordx4 v[184:185], off
	v_lshl_add_u64 v[184:185], v[214:215], 0, s[2:3]
	s_mov_b32 m0, s43
	s_nop 0
	global_load_lds_dwordx4 v[184:185], off
	s_waitcnt vmcnt(8)
	s_waitcnt lgkmcnt(0)
	s_setprio 1
	s_barrier
	s_waitcnt lgkmcnt(0)
	v_mfma_f32_16x16x32_bf16 v[62:65], v[122:125], v[172:175], v[62:65]
	v_mfma_f32_16x16x32_bf16 v[58:61], v[138:141], v[172:175], v[58:61]
	v_mfma_f32_16x16x32_bf16 v[46:49], v[122:125], v[180:183], v[46:49]
	v_mfma_f32_16x16x32_bf16 v[42:45], v[138:141], v[180:183], v[42:45]
	v_mfma_f32_16x16x32_bf16 v[30:33], v[122:125], v[194:197], v[30:33]
	v_mfma_f32_16x16x32_bf16 v[26:29], v[138:141], v[194:197], v[26:29]
	v_mfma_f32_16x16x32_bf16 v[14:17], v[122:125], v[202:205], v[14:17]
	v_mfma_f32_16x16x32_bf16 v[10:13], v[138:141], v[202:205], v[10:13]
	v_mfma_f32_16x16x32_bf16 v[62:65], v[130:133], v[176:179], v[62:65]
	v_mfma_f32_16x16x32_bf16 v[58:61], v[142:145], v[176:179], v[58:61]
	v_mfma_f32_16x16x32_bf16 v[46:49], v[130:133], v[190:193], v[46:49]
	v_mfma_f32_16x16x32_bf16 v[42:45], v[142:145], v[190:193], v[42:45]
	v_mfma_f32_16x16x32_bf16 v[30:33], v[130:133], v[198:201], v[30:33]
	v_mfma_f32_16x16x32_bf16 v[26:29], v[142:145], v[198:201], v[26:29]
	v_mfma_f32_16x16x32_bf16 v[14:17], v[130:133], v[206:209], v[14:17]
	v_mfma_f32_16x16x32_bf16 v[10:13], v[142:145], v[206:209], v[10:13]
	s_setprio 0
	s_setprio 1
	v_mfma_f32_16x16x32_bf16 v[54:57], v[146:149], v[172:175], v[54:57]
	v_mfma_f32_16x16x32_bf16 v[50:53], v[154:157], v[172:175], v[50:53]
	v_mfma_f32_16x16x32_bf16 v[38:41], v[146:149], v[180:183], v[38:41]
	v_mfma_f32_16x16x32_bf16 v[34:37], v[154:157], v[180:183], v[34:37]
	v_mfma_f32_16x16x32_bf16 v[22:25], v[146:149], v[194:197], v[22:25]
	v_mfma_f32_16x16x32_bf16 v[18:21], v[154:157], v[194:197], v[18:21]
	v_mfma_f32_16x16x32_bf16 v[6:9], v[146:149], v[202:205], v[6:9]
	v_mfma_f32_16x16x32_bf16 v[2:5], v[154:157], v[202:205], v[2:5]
	v_mfma_f32_16x16x32_bf16 v[54:57], v[150:153], v[176:179], v[54:57]
	v_mfma_f32_16x16x32_bf16 v[50:53], v[168:171], v[176:179], v[50:53]
	v_mfma_f32_16x16x32_bf16 v[38:41], v[150:153], v[190:193], v[38:41]
	v_mfma_f32_16x16x32_bf16 v[34:37], v[168:171], v[190:193], v[34:37]
	v_mfma_f32_16x16x32_bf16 v[22:25], v[150:153], v[198:201], v[22:25]
	v_mfma_f32_16x16x32_bf16 v[18:21], v[168:171], v[198:201], v[18:21]
	v_mfma_f32_16x16x32_bf16 v[6:9], v[150:153], v[206:209], v[6:9]
	v_mfma_f32_16x16x32_bf16 v[2:5], v[168:171], v[206:209], v[2:5]
	s_barrier
	s_setprio 0
	s_add_i32 s51, s51, 2
	s_add_u32 s49, s49, 0x100
	s_addc_u32 s50, s50, 0
	s_cmp_gt_u32 s51, 41
	s_mov_b64 s[8:9], s[10:11]
	s_cbranch_scc0 .LBB0_504
	s_and_b64 vcc, exec, s[18:19]
	s_cbranch_vccz .LBB0_507
	s_barrier
